# removed the 20 back-to-back s_setprio 0 / s_setprio 1 pairs between the two MFMA groups of each GEMM sub-phase
# speedup vs baseline: 1.0056x; 1.0056x over previous
; #define PG8_STAGE(bufoff, gbase, voff) do { _Pragma("unroll") for (int _i = 0; _i < 2; ++_i) \
;         __builtin_amdgcn_global_load_lds((const unsigned*)((const char*)(gbase) + (voff)[_i]), (LAS unsigned*)(lds + (bufoff) + ldsw + _i * 8192), 16, 0, 0); } while (0)
; #define PG8_LDA(dst, b, h) do { _Pragma("unroll") for (int m = 0; m < 4; ++m) _Pragma("unroll") for (int k = 0; k < 2; ++k) dst[m][k] = *(const LAS bf16x8*)(lds + PG8_SA(b, h) + aoff + m * 2048 + k * 1024); } while (0)
; #define PG8_LDB(dst, b, h) do { _Pragma("unroll") for (int n = 0; n < 2; ++n) _Pragma("unroll") for (int k = 0; k < 2; ++k) dst[n][k] = *(const LAS bf16x8*)(lds + PG8_SB(b, h) + boff + n * 2048 + k * 1024); } while (0)
; #define PG8_MMA(ai, bj, At, Bt) do { __builtin_amdgcn_s_setprio(1); _Pragma("unroll") for (int m = 0; m < 4; ++m) _Pragma("unroll") for (int n = 0; n < 2; ++n) _Pragma("unroll") for (int k = 0; k < 2; ++k) \
;         acc[ai][bj][m][n] = __builtin_amdgcn_mfma_f32_16x16x32_bf16(Bt[n][k], At[m][k], acc[ai][bj][m][n], 0, 0, 0); __builtin_amdgcn_s_setprio(0); } while (0)
; #define PG8_WAIT_V(n) asm volatile("s_waitcnt vmcnt(" #n ")" ::: "memory")
; #define PG8_WAIT_L(n) asm volatile("s_waitcnt lgkmcnt(" #n ")" ::: "memory")
; #define PG8_BAR __builtin_amdgcn_s_barrier()
; #define PG8_SCHED __builtin_amdgcn_sched_barrier(0)
; template <class Epi, class Sched>
; DI void gemm_phase(const int wv, LAS unsigned char* lds, const int lda, const int ldb, const int K, const Sched& S, const Epi& E) {
;     ...
;             const char* a1 = cA + (size_t)(t + 1) * kstep;
;             const char* a2 = last ? nA : cA + (size_t)(t + 2) * kstep; const char* b2 = last ? nB : cB + (size_t)(t + 2) * kstep;
;             const char* a3 = a2 + kstep; const char* b3 = b2 + kstep;
;             PG8_LDB(B0, 0, 0); PG8_LDB(B1, 0, 1); PG8_SCHED; PG8_LDA(At, 0, 0); PG8_STAGE(PG8_SA(1, 1), a1 + hstepA, voffA);
;             PG8_WAIT_V(8); PG8_WAIT_L(0); PG8_BAR; PG8_MMA(0, 0, At, B0); PG8_MMA(0, 1, At, B1); PG8_BAR; PG8_SCHED;
;             PG8_LDA(At, 0, 1); PG8_STAGE(PG8_SB(0, 0), b2, voffB); PG8_STAGE(PG8_SB(0, 1), b2 + hstepB, voffB); PG8_STAGE(PG8_SA(0, 0), a2, voffA);
;             PG8_WAIT_V(8); PG8_WAIT_L(0); PG8_BAR; PG8_MMA(1, 0, At, B0); PG8_MMA(1, 1, At, B1); PG8_BAR; PG8_SCHED;
.LBB0_285:
	s_add_u32 s20, s18, 0xfff80080
	s_addc_u32 s21, s19, -1
	s_add_i32 s42, 0, 0x10000
	s_cmp_eq_u32 s41, 28
	s_cselect_b32 s23, s15, s21
	s_cselect_b32 s22, s14, s20
	v_add_u32_e32 v143, s42, v139
	s_cselect_b32 s21, s17, s40
	s_cselect_b32 s20, s16, s13
	s_add_i32 s44, 0, 0x14000
	ds_read_b128 v[144:147], v143
	ds_read_b128 v[148:151], v143 offset:1024
	ds_read_b128 v[152:155], v143 offset:2048
	ds_read_b128 v[156:159], v143 offset:3072
	v_add_u32_e32 v143, s44, v139
	ds_read_b128 v[168:171], v143
	ds_read_b128 v[172:175], v143 offset:1024
	ds_read_b128 v[176:179], v143 offset:2048
	ds_read_b128 v[180:183], v143 offset:3072
	v_lshl_add_u64 v[162:163], s[18:19], 0, v[136:137]
	s_add_i32 m0, s29, 0xc000
	ds_read_b128 v[184:187], v142
	ds_read_b128 v[188:191], v142 offset:1024
	ds_read_b128 v[192:195], v142 offset:2048
	ds_read_b128 v[196:199], v142 offset:3072
	ds_read_b128 v[210:213], v142 offset:4096
	ds_read_b128 v[214:217], v142 offset:5120
	ds_read_b128 v[218:221], v142 offset:6144
	ds_read_b128 v[222:225], v142 offset:7168
	global_load_lds_dwordx4 v[162:163], off
	v_lshl_add_u64 v[162:163], s[18:19], 0, v[134:135]
	s_add_i32 m0, s29, 0xe000
	s_nop 0
	global_load_lds_dwordx4 v[162:163], off
	s_waitcnt vmcnt(8)
	s_waitcnt lgkmcnt(0)
	s_barrier
	s_setprio 1
	s_waitcnt lgkmcnt(0)
	v_mfma_f32_16x16x32_bf16 v[124:127], v[144:147], v[184:187], v[124:127]
	v_mfma_f32_16x16x32_bf16 v[120:123], v[152:155], v[184:187], v[120:123]
	v_mfma_f32_16x16x32_bf16 v[116:119], v[144:147], v[192:195], v[116:119]
	v_mfma_f32_16x16x32_bf16 v[112:115], v[152:155], v[192:195], v[112:115]
	v_mfma_f32_16x16x32_bf16 v[100:103], v[144:147], v[210:213], v[100:103]
	v_mfma_f32_16x16x32_bf16 v[96:99], v[152:155], v[210:213], v[96:99]
	v_mfma_f32_16x16x32_bf16 v[88:91], v[144:147], v[218:221], v[88:91]
	v_mfma_f32_16x16x32_bf16 v[80:83], v[152:155], v[218:221], v[80:83]
	v_mfma_f32_16x16x32_bf16 v[124:127], v[148:151], v[188:191], v[124:127]
	v_mfma_f32_16x16x32_bf16 v[120:123], v[156:159], v[188:191], v[120:123]
	v_mfma_f32_16x16x32_bf16 v[116:119], v[148:151], v[196:199], v[116:119]
	v_mfma_f32_16x16x32_bf16 v[112:115], v[156:159], v[196:199], v[112:115]
	v_mfma_f32_16x16x32_bf16 v[100:103], v[148:151], v[214:217], v[100:103]
	v_mfma_f32_16x16x32_bf16 v[96:99], v[156:159], v[214:217], v[96:99]
	v_mfma_f32_16x16x32_bf16 v[88:91], v[148:151], v[222:225], v[88:91]
	v_mfma_f32_16x16x32_bf16 v[80:83], v[156:159], v[222:225], v[80:83]
	v_mfma_f32_16x16x32_bf16 v[108:111], v[168:171], v[184:187], v[108:111]
	v_mfma_f32_16x16x32_bf16 v[104:107], v[176:179], v[184:187], v[104:107]
	v_mfma_f32_16x16x32_bf16 v[92:95], v[168:171], v[192:195], v[92:95]
	v_mfma_f32_16x16x32_bf16 v[84:87], v[176:179], v[192:195], v[84:87]
	v_mfma_f32_16x16x32_bf16 v[76:79], v[168:171], v[210:213], v[76:79]
	v_mfma_f32_16x16x32_bf16 v[72:75], v[176:179], v[210:213], v[72:75]
	v_mfma_f32_16x16x32_bf16 v[68:71], v[168:171], v[218:221], v[68:71]
	v_mfma_f32_16x16x32_bf16 v[64:67], v[176:179], v[218:221], v[64:67]
	v_mfma_f32_16x16x32_bf16 v[108:111], v[172:175], v[188:191], v[108:111]
	v_mfma_f32_16x16x32_bf16 v[104:107], v[180:183], v[188:191], v[104:107]
	v_mfma_f32_16x16x32_bf16 v[92:95], v[172:175], v[196:199], v[92:95]
	v_mfma_f32_16x16x32_bf16 v[84:87], v[180:183], v[196:199], v[84:87]
	v_mfma_f32_16x16x32_bf16 v[76:79], v[172:175], v[214:217], v[76:79]
	v_mfma_f32_16x16x32_bf16 v[72:75], v[180:183], v[214:217], v[72:75]
	v_mfma_f32_16x16x32_bf16 v[68:71], v[172:175], v[222:225], v[68:71]
	v_mfma_f32_16x16x32_bf16 v[64:67], v[180:183], v[222:225], v[64:67]
	s_setprio 0
	s_barrier
	s_add_i32 s42, s42, s28
	v_lshl_add_u64 v[162:163], s[20:21], 0, v[160:161]
	s_mov_b32 m0, s42
	ds_read_b128 v[184:187], v142 offset:16384
	ds_read_b128 v[188:191], v142 offset:17408
	ds_read_b128 v[192:195], v142 offset:18432
	ds_read_b128 v[196:199], v142 offset:19456
	ds_read_b128 v[210:213], v142 offset:20480
	ds_read_b128 v[214:217], v142 offset:21504
	ds_read_b128 v[218:221], v142 offset:22528
	ds_read_b128 v[222:225], v142 offset:23552
	global_load_lds_dwordx4 v[162:163], off
	s_add_i32 m0, s42, 0x2000
	s_add_u32 s42, s20, 0x80000
	v_lshl_add_u64 v[164:165], s[20:21], 0, v[128:129]
	s_addc_u32 s43, s21, 0
	s_add_i32 s44, s44, s28
	global_load_lds_dwordx4 v[164:165], off
	v_lshl_add_u64 v[226:227], s[42:43], 0, v[160:161]
	s_mov_b32 m0, s44
	v_lshl_add_u64 v[228:229], s[22:23], 0, v[130:131]
	global_load_lds_dwordx4 v[226:227], off
	v_lshl_add_u64 v[226:227], s[42:43], 0, v[128:129]
	s_add_i32 m0, s44, 0x2000
	s_nop 0
	global_load_lds_dwordx4 v[226:227], off
	v_lshl_add_u64 v[226:227], s[22:23], 0, v[132:133]
	s_mov_b32 m0, s29
	s_nop 0
	global_load_lds_dwordx4 v[226:227], off
	s_mov_b32 m0, s30
	s_nop 0
	global_load_lds_dwordx4 v[228:229], off
	s_waitcnt vmcnt(8)
	s_waitcnt lgkmcnt(0)
	s_barrier
; #define PG8_STAGE(bufoff, gbase, voff) do { _Pragma("unroll") for (int _i = 0; _i < 2; ++_i) \
;         __builtin_amdgcn_global_load_lds((const unsigned*)((const char*)(gbase) + (voff)[_i]), (LAS unsigned*)(lds + (bufoff) + ldsw + _i * 8192), 16, 0, 0); } while (0)
; #define PG8_LDA(dst, b, h) do { _Pragma("unroll") for (int m = 0; m < 4; ++m) _Pragma("unroll") for (int k = 0; k < 2; ++k) dst[m][k] = *(const LAS bf16x8*)(lds + PG8_SA(b, h) + aoff + m * 2048 + k * 1024); } while (0)
; #define PG8_LDB(dst, b, h) do { _Pragma("unroll") for (int n = 0; n < 2; ++n) _Pragma("unroll") for (int k = 0; k < 2; ++k) dst[n][k] = *(const LAS bf16x8*)(lds + PG8_SB(b, h) + boff + n * 2048 + k * 1024); } while (0)
; #define PG8_MMA(ai, bj, At, Bt) do { __builtin_amdgcn_s_setprio(1); _Pragma("unroll") for (int m = 0; m < 4; ++m) _Pragma("unroll") for (int n = 0; n < 2; ++n) _Pragma("unroll") for (int k = 0; k < 2; ++k) \
;         acc[ai][bj][m][n] = __builtin_amdgcn_mfma_f32_16x16x32_bf16(Bt[n][k], At[m][k], acc[ai][bj][m][n], 0, 0, 0); __builtin_amdgcn_s_setprio(0); } while (0)
; #define PG8_WAIT_V(n) asm volatile("s_waitcnt vmcnt(" #n ")" ::: "memory")
; #define PG8_WAIT_L(n) asm volatile("s_waitcnt lgkmcnt(" #n ")" ::: "memory")
; #define PG8_BAR __builtin_amdgcn_s_barrier()
; #define PG8_SCHED __builtin_amdgcn_sched_barrier(0)
; template <class Epi, class Sched>
; DI void gemm_phase(const int wv, LAS unsigned char* lds, const int lda, const int ldb, const int K, const Sched& S, const Epi& E) {
;     ...
;             PG8_WAIT_V(8); PG8_WAIT_L(0); PG8_BAR; PG8_MMA(1, 0, At, B0); PG8_MMA(1, 1, At, B1); PG8_BAR; PG8_SCHED;
;             PG8_LDB(B0, 1, 0); PG8_LDB(B1, 1, 1); PG8_SCHED; PG8_LDA(At, 1, 0); PG8_STAGE(PG8_SA(0, 1), a2 + hstepA, voffA);
;             PG8_WAIT_V(8); PG8_WAIT_L(0); PG8_BAR; PG8_MMA(0, 0, At, B0); PG8_MMA(0, 1, At, B1); PG8_BAR; PG8_SCHED;
	s_setprio 1
	s_waitcnt lgkmcnt(0)
	v_mfma_f32_16x16x32_bf16 v[60:63], v[144:147], v[184:187], v[60:63]
	v_mfma_f32_16x16x32_bf16 v[56:59], v[152:155], v[184:187], v[56:59]
	v_mfma_f32_16x16x32_bf16 v[52:55], v[144:147], v[192:195], v[52:55]
	v_mfma_f32_16x16x32_bf16 v[48:51], v[152:155], v[192:195], v[48:51]
	v_mfma_f32_16x16x32_bf16 v[44:47], v[144:147], v[210:213], v[44:47]
	v_mfma_f32_16x16x32_bf16 v[36:39], v[152:155], v[210:213], v[36:39]
	v_mfma_f32_16x16x32_bf16 v[28:31], v[144:147], v[218:221], v[28:31]
	v_mfma_f32_16x16x32_bf16 v[20:23], v[152:155], v[218:221], v[20:23]
	v_mfma_f32_16x16x32_bf16 v[60:63], v[148:151], v[188:191], v[60:63]
	v_mfma_f32_16x16x32_bf16 v[56:59], v[156:159], v[188:191], v[56:59]
	v_mfma_f32_16x16x32_bf16 v[52:55], v[148:151], v[196:199], v[52:55]
	v_mfma_f32_16x16x32_bf16 v[48:51], v[156:159], v[196:199], v[48:51]
	v_mfma_f32_16x16x32_bf16 v[44:47], v[148:151], v[214:217], v[44:47]
	v_mfma_f32_16x16x32_bf16 v[36:39], v[156:159], v[214:217], v[36:39]
	v_mfma_f32_16x16x32_bf16 v[28:31], v[148:151], v[222:225], v[28:31]
	v_mfma_f32_16x16x32_bf16 v[20:23], v[156:159], v[222:225], v[20:23]
	v_mfma_f32_16x16x32_bf16 v[40:43], v[168:171], v[184:187], v[40:43]
	v_mfma_f32_16x16x32_bf16 v[32:35], v[176:179], v[184:187], v[32:35]
	v_mfma_f32_16x16x32_bf16 v[24:27], v[168:171], v[192:195], v[24:27]
	v_mfma_f32_16x16x32_bf16 v[16:19], v[176:179], v[192:195], v[16:19]
	v_mfma_f32_16x16x32_bf16 v[12:15], v[168:171], v[210:213], v[12:15]
	v_mfma_f32_16x16x32_bf16 v[8:11], v[176:179], v[210:213], v[8:11]
	v_mfma_f32_16x16x32_bf16 v[4:7], v[168:171], v[218:221], v[4:7]
	v_mfma_f32_16x16x32_bf16 v[0:3], v[176:179], v[218:221], v[0:3]
	v_mfma_f32_16x16x32_bf16 v[40:43], v[172:175], v[188:191], v[40:43]
	v_mfma_f32_16x16x32_bf16 v[32:35], v[180:183], v[188:191], v[32:35]
	v_mfma_f32_16x16x32_bf16 v[24:27], v[172:175], v[196:199], v[24:27]
	v_mfma_f32_16x16x32_bf16 v[16:19], v[180:183], v[196:199], v[16:19]
	v_mfma_f32_16x16x32_bf16 v[12:15], v[172:175], v[214:217], v[12:15]
	v_mfma_f32_16x16x32_bf16 v[8:11], v[180:183], v[214:217], v[8:11]
	v_mfma_f32_16x16x32_bf16 v[4:7], v[172:175], v[222:225], v[4:7]
	v_mfma_f32_16x16x32_bf16 v[0:3], v[180:183], v[222:225], v[0:3]
	s_setprio 0
	s_barrier
	s_add_i32 s42, 0, 0x18000
	v_add_u32_e32 v143, s42, v139
	s_add_i32 s43, 0, 0x1c000
	ds_read_b128 v[144:147], v143
	ds_read_b128 v[148:151], v143 offset:1024
	ds_read_b128 v[152:155], v143 offset:2048
	ds_read_b128 v[156:159], v143 offset:3072
	v_add_u32_e32 v143, s43, v139
	ds_read_b128 v[168:171], v143
	ds_read_b128 v[172:175], v143 offset:1024
	ds_read_b128 v[176:179], v143 offset:2048
	ds_read_b128 v[180:183], v143 offset:3072
	s_add_u32 s22, s22, 0x80000
	s_addc_u32 s23, s23, 0
	s_mov_b32 m0, s31
	v_lshl_add_u64 v[230:231], s[22:23], 0, v[132:133]
	ds_read_b128 v[184:187], v142 offset:32768
	ds_read_b128 v[188:191], v142 offset:33792
	ds_read_b128 v[192:195], v142 offset:34816
	ds_read_b128 v[196:199], v142 offset:35840
	ds_read_b128 v[210:213], v142 offset:36864
	ds_read_b128 v[214:217], v142 offset:37888
	ds_read_b128 v[218:221], v142 offset:38912
	ds_read_b128 v[222:225], v142 offset:39936
	global_load_lds_dwordx4 v[230:231], off
	v_lshl_add_u64 v[230:231], s[22:23], 0, v[130:131]
	s_mov_b32 m0, s34
	s_nop 0
	global_load_lds_dwordx4 v[230:231], off
	s_waitcnt vmcnt(8)
	s_waitcnt lgkmcnt(0)
	s_barrier
	s_setprio 1
	s_waitcnt lgkmcnt(0)
	v_mfma_f32_16x16x32_bf16 v[124:127], v[144:147], v[184:187], v[124:127]
	v_mfma_f32_16x16x32_bf16 v[120:123], v[152:155], v[184:187], v[120:123]
	v_mfma_f32_16x16x32_bf16 v[116:119], v[144:147], v[192:195], v[116:119]
	v_mfma_f32_16x16x32_bf16 v[112:115], v[152:155], v[192:195], v[112:115]
	v_mfma_f32_16x16x32_bf16 v[100:103], v[144:147], v[210:213], v[100:103]
	v_mfma_f32_16x16x32_bf16 v[96:99], v[152:155], v[210:213], v[96:99]
	v_mfma_f32_16x16x32_bf16 v[88:91], v[144:147], v[218:221], v[88:91]
	v_mfma_f32_16x16x32_bf16 v[80:83], v[152:155], v[218:221], v[80:83]
	v_mfma_f32_16x16x32_bf16 v[124:127], v[148:151], v[188:191], v[124:127]
	v_mfma_f32_16x16x32_bf16 v[120:123], v[156:159], v[188:191], v[120:123]
	v_mfma_f32_16x16x32_bf16 v[116:119], v[148:151], v[196:199], v[116:119]
	v_mfma_f32_16x16x32_bf16 v[112:115], v[156:159], v[196:199], v[112:115]
	v_mfma_f32_16x16x32_bf16 v[100:103], v[148:151], v[214:217], v[100:103]
	v_mfma_f32_16x16x32_bf16 v[96:99], v[156:159], v[214:217], v[96:99]
	v_mfma_f32_16x16x32_bf16 v[88:91], v[148:151], v[222:225], v[88:91]
	v_mfma_f32_16x16x32_bf16 v[80:83], v[156:159], v[222:225], v[80:83]
	v_mfma_f32_16x16x32_bf16 v[108:111], v[168:171], v[184:187], v[108:111]
	v_mfma_f32_16x16x32_bf16 v[104:107], v[176:179], v[184:187], v[104:107]
	v_mfma_f32_16x16x32_bf16 v[92:95], v[168:171], v[192:195], v[92:95]
	v_mfma_f32_16x16x32_bf16 v[84:87], v[176:179], v[192:195], v[84:87]
	v_mfma_f32_16x16x32_bf16 v[76:79], v[168:171], v[210:213], v[76:79]
	v_mfma_f32_16x16x32_bf16 v[72:75], v[176:179], v[210:213], v[72:75]
	v_mfma_f32_16x16x32_bf16 v[68:71], v[168:171], v[218:221], v[68:71]
	v_mfma_f32_16x16x32_bf16 v[64:67], v[176:179], v[218:221], v[64:67]
	v_mfma_f32_16x16x32_bf16 v[108:111], v[172:175], v[188:191], v[108:111]
	v_mfma_f32_16x16x32_bf16 v[104:107], v[180:183], v[188:191], v[104:107]
	v_mfma_f32_16x16x32_bf16 v[92:95], v[172:175], v[196:199], v[92:95]
	v_mfma_f32_16x16x32_bf16 v[84:87], v[180:183], v[196:199], v[84:87]
	v_mfma_f32_16x16x32_bf16 v[76:79], v[172:175], v[214:217], v[76:79]
	v_mfma_f32_16x16x32_bf16 v[72:75], v[180:183], v[214:217], v[72:75]
	v_mfma_f32_16x16x32_bf16 v[68:71], v[172:175], v[222:225], v[68:71]
	v_mfma_f32_16x16x32_bf16 v[64:67], v[180:183], v[222:225], v[64:67]
	s_setprio 0
	s_barrier
; #define PG8_STAGE(bufoff, gbase, voff) do { _Pragma("unroll") for (int _i = 0; _i < 2; ++_i) \
;         __builtin_amdgcn_global_load_lds((const unsigned*)((const char*)(gbase) + (voff)[_i]), (LAS unsigned*)(lds + (bufoff) + ldsw + _i * 8192), 16, 0, 0); } while (0)
; #define PG8_LDA(dst, b, h) do { _Pragma("unroll") for (int m = 0; m < 4; ++m) _Pragma("unroll") for (int k = 0; k < 2; ++k) dst[m][k] = *(const LAS bf16x8*)(lds + PG8_SA(b, h) + aoff + m * 2048 + k * 1024); } while (0)
; #define PG8_MMA(ai, bj, At, Bt) do { __builtin_amdgcn_s_setprio(1); _Pragma("unroll") for (int m = 0; m < 4; ++m) _Pragma("unroll") for (int n = 0; n < 2; ++n) _Pragma("unroll") for (int k = 0; k < 2; ++k) \
;         acc[ai][bj][m][n] = __builtin_amdgcn_mfma_f32_16x16x32_bf16(Bt[n][k], At[m][k], acc[ai][bj][m][n], 0, 0, 0); __builtin_amdgcn_s_setprio(0); } while (0)
; #define PG8_WAIT_V(n) asm volatile("s_waitcnt vmcnt(" #n ")" ::: "memory")
; #define PG8_WAIT_L(n) asm volatile("s_waitcnt lgkmcnt(" #n ")" ::: "memory")
; #define PG8_BAR __builtin_amdgcn_s_barrier()
; #define PG8_SCHED __builtin_amdgcn_sched_barrier(0)
; template <class Epi, class Sched>
; DI void gemm_phase(const int wv, LAS unsigned char* lds, const int lda, const int ldb, const int K, const Sched& S, const Epi& E) {
;     ...
;             PG8_LDA(At, 1, 1); PG8_STAGE(PG8_SB(1, 0), b3, voffB); PG8_STAGE(PG8_SB(1, 1), b3 + hstepB, voffB); PG8_STAGE(PG8_SA(1, 0), a3, voffA);
;             PG8_WAIT_V(8); PG8_WAIT_L(0); PG8_BAR; PG8_MMA(1, 0, At, B0); PG8_MMA(1, 1, At, B1); PG8_BAR; PG8_SCHED;
;         }
;         if (wr == 0) PG8_BAR;
	s_add_i32 s22, s42, s28
	v_lshl_add_u64 v[162:163], v[162:163], 0, s[78:79]
	s_mov_b32 m0, s22
	ds_read_b128 v[184:187], v142 offset:49152
	ds_read_b128 v[188:191], v142 offset:50176
	ds_read_b128 v[192:195], v142 offset:51200
	ds_read_b128 v[196:199], v142 offset:52224
	ds_read_b128 v[210:213], v142 offset:53248
	ds_read_b128 v[214:217], v142 offset:54272
	ds_read_b128 v[218:221], v142 offset:55296
	ds_read_b128 v[222:225], v142 offset:56320
	global_load_lds_dwordx4 v[162:163], off
	s_add_i32 m0, s22, 0x2000
	s_add_u32 s20, s20, 0x80080
	v_lshl_add_u64 v[162:163], v[164:165], 0, s[78:79]
	s_addc_u32 s21, s21, 0
	s_add_i32 s22, s43, s28
	global_load_lds_dwordx4 v[162:163], off
	v_lshl_add_u64 v[162:163], s[20:21], 0, v[160:161]
	s_mov_b32 m0, s22
	s_nop 0
	global_load_lds_dwordx4 v[162:163], off
	v_lshl_add_u64 v[162:163], s[20:21], 0, v[128:129]
	s_add_i32 m0, s22, 0x2000
	s_nop 0
	global_load_lds_dwordx4 v[162:163], off
	v_lshl_add_u64 v[162:163], v[226:227], 0, s[78:79]
	s_mov_b32 m0, s35
	s_nop 0
	global_load_lds_dwordx4 v[162:163], off
	v_lshl_add_u64 v[162:163], v[228:229], 0, s[78:79]
	s_mov_b32 m0, s36
	s_nop 0
	global_load_lds_dwordx4 v[162:163], off
	s_waitcnt vmcnt(8)
	s_waitcnt lgkmcnt(0)
	s_barrier
	s_setprio 1
	s_waitcnt lgkmcnt(0)
	v_mfma_f32_16x16x32_bf16 v[60:63], v[144:147], v[184:187], v[60:63]
	v_mfma_f32_16x16x32_bf16 v[56:59], v[152:155], v[184:187], v[56:59]
	v_mfma_f32_16x16x32_bf16 v[52:55], v[144:147], v[192:195], v[52:55]
	v_mfma_f32_16x16x32_bf16 v[48:51], v[152:155], v[192:195], v[48:51]
	v_mfma_f32_16x16x32_bf16 v[44:47], v[144:147], v[210:213], v[44:47]
	v_mfma_f32_16x16x32_bf16 v[36:39], v[152:155], v[210:213], v[36:39]
	v_mfma_f32_16x16x32_bf16 v[28:31], v[144:147], v[218:221], v[28:31]
	v_mfma_f32_16x16x32_bf16 v[20:23], v[152:155], v[218:221], v[20:23]
	v_mfma_f32_16x16x32_bf16 v[60:63], v[148:151], v[188:191], v[60:63]
	v_mfma_f32_16x16x32_bf16 v[56:59], v[156:159], v[188:191], v[56:59]
	v_mfma_f32_16x16x32_bf16 v[52:55], v[148:151], v[196:199], v[52:55]
	v_mfma_f32_16x16x32_bf16 v[48:51], v[156:159], v[196:199], v[48:51]
	v_mfma_f32_16x16x32_bf16 v[44:47], v[148:151], v[214:217], v[44:47]
	v_mfma_f32_16x16x32_bf16 v[36:39], v[156:159], v[214:217], v[36:39]
	v_mfma_f32_16x16x32_bf16 v[28:31], v[148:151], v[222:225], v[28:31]
	v_mfma_f32_16x16x32_bf16 v[20:23], v[156:159], v[222:225], v[20:23]
	v_mfma_f32_16x16x32_bf16 v[40:43], v[168:171], v[184:187], v[40:43]
	v_mfma_f32_16x16x32_bf16 v[32:35], v[176:179], v[184:187], v[32:35]
	v_mfma_f32_16x16x32_bf16 v[24:27], v[168:171], v[192:195], v[24:27]
	v_mfma_f32_16x16x32_bf16 v[16:19], v[176:179], v[192:195], v[16:19]
	v_mfma_f32_16x16x32_bf16 v[12:15], v[168:171], v[210:213], v[12:15]
	v_mfma_f32_16x16x32_bf16 v[8:11], v[176:179], v[210:213], v[8:11]
	v_mfma_f32_16x16x32_bf16 v[4:7], v[168:171], v[218:221], v[4:7]
	v_mfma_f32_16x16x32_bf16 v[0:3], v[176:179], v[218:221], v[0:3]
	v_mfma_f32_16x16x32_bf16 v[40:43], v[172:175], v[188:191], v[40:43]
	v_mfma_f32_16x16x32_bf16 v[32:35], v[180:183], v[188:191], v[32:35]
	v_mfma_f32_16x16x32_bf16 v[24:27], v[172:175], v[196:199], v[24:27]
	v_mfma_f32_16x16x32_bf16 v[16:19], v[180:183], v[196:199], v[16:19]
	v_mfma_f32_16x16x32_bf16 v[12:15], v[172:175], v[214:217], v[12:15]
	v_mfma_f32_16x16x32_bf16 v[8:11], v[180:183], v[214:217], v[8:11]
	v_mfma_f32_16x16x32_bf16 v[4:7], v[172:175], v[222:225], v[4:7]
	v_mfma_f32_16x16x32_bf16 v[0:3], v[180:183], v[222:225], v[0:3]
	s_setprio 0
	s_barrier
	s_add_i32 s41, s41, 2
	s_add_u32 s13, s13, 0x100
	s_addc_u32 s40, s40, 0
	s_add_u32 s18, s18, 0x100
	s_addc_u32 s19, s19, 0
	s_cmp_gt_u32 s41, 29
	s_cbranch_scc0 .LBB0_285
	s_and_b64 vcc, exec, s[10:11]
	s_cbranch_vccz .LBB0_288
	s_barrier

; #define PG8_STAGE(bufoff, gbase, voff) do { _Pragma("unroll") for (int _i = 0; _i < 2; ++_i) \
;         __builtin_amdgcn_global_load_lds((const unsigned*)((const char*)(gbase) + (voff)[_i]), (LAS unsigned*)(lds + (bufoff) + ldsw + _i * 8192), 16, 0, 0); } while (0)
; #define PG8_LDA(dst, b, h) do { _Pragma("unroll") for (int m = 0; m < 4; ++m) _Pragma("unroll") for (int k = 0; k < 2; ++k) dst[m][k] = *(const LAS bf16x8*)(lds + PG8_SA(b, h) + aoff + m * 2048 + k * 1024); } while (0)
; #define PG8_LDB(dst, b, h) do { _Pragma("unroll") for (int n = 0; n < 2; ++n) _Pragma("unroll") for (int k = 0; k < 2; ++k) dst[n][k] = *(const LAS bf16x8*)(lds + PG8_SB(b, h) + boff + n * 2048 + k * 1024); } while (0)
; #define PG8_MMA(ai, bj, At, Bt) do { __builtin_amdgcn_s_setprio(1); _Pragma("unroll") for (int m = 0; m < 4; ++m) _Pragma("unroll") for (int n = 0; n < 2; ++n) _Pragma("unroll") for (int k = 0; k < 2; ++k) \
;         acc[ai][bj][m][n] = __builtin_amdgcn_mfma_f32_16x16x32_bf16(Bt[n][k], At[m][k], acc[ai][bj][m][n], 0, 0, 0); __builtin_amdgcn_s_setprio(0); } while (0)
; #define PG8_WAIT_V(n) asm volatile("s_waitcnt vmcnt(" #n ")" ::: "memory")
; template <class Epi, class Sched>
; DI void gemm_phase(const int wv, LAS unsigned char* lds, const int lda, const int ldb, const int K, const Sched& S, const Epi& E) {
;     ...
;         const bool has_next = S.next(ui + 1, nxt);
;         const char* nA = has_next ? nxt.a : cA; const char* nB = has_next ? nxt.b : cB;
; #pragma unroll 1
;         for (int t = 0; t < nt; t += 2) {
;             const bool last = (t == nt - 2);
;             const char* a1 = cA + (size_t)(t + 1) * kstep;
;             const char* a2 = last ? nA : cA + (size_t)(t + 2) * kstep; const char* b2 = last ? nB : cB + (size_t)(t + 2) * kstep;
;             const char* a3 = a2 + kstep; const char* b3 = b2 + kstep;
;             PG8_LDB(B0, 0, 0); PG8_LDB(B1, 0, 1); PG8_SCHED; PG8_LDA(At, 0, 0); PG8_STAGE(PG8_SA(1, 1), a1 + hstepA, voffA);
;             PG8_WAIT_V(8); PG8_WAIT_L(0); PG8_BAR; PG8_MMA(0, 0, At, B0); PG8_MMA(0, 1, At, B1); PG8_BAR; PG8_SCHED;
;             PG8_LDA(At, 0, 1); PG8_STAGE(PG8_SB(0, 0), b2, voffB); PG8_STAGE(PG8_SB(0, 1), b2 + hstepB, voffB); PG8_STAGE(PG8_SA(0, 0), a2, voffA);
;             PG8_WAIT_V(8); PG8_WAIT_L(0); PG8_BAR; PG8_MMA(1, 0, At, B0); PG8_MMA(1, 1, At, B1); PG8_BAR; PG8_SCHED;
.LBB0_516:
	s_add_u32 s14, s2, s8
	s_addc_u32 s15, s3, s9
	s_add_u32 s12, s14, 0x100
	s_addc_u32 s13, s15, 0
	s_and_b64 s[10:11], s[6:7], exec
	s_cselect_b32 s11, s3, s13
	s_cselect_b32 s10, s2, s12
	s_add_u32 s8, s0, s8
	s_addc_u32 s9, s1, s9
	s_add_u32 s8, s8, 0x100
	s_addc_u32 s9, s9, 0
	s_add_i32 s39, 0, 0x10000
	s_and_b64 s[6:7], s[6:7], exec
	s_cselect_b32 s13, s1, s9
	s_cselect_b32 s12, s0, s8
	s_add_i32 s7, 0, 0x14000
	s_add_u32 s16, s14, 0x40080
	s_addc_u32 s17, s15, 0
	s_add_i32 s38, s39, s21
	s_add_i32 m0, s22, 0xc000
	s_add_i32 s41, s22, 0xe000
	s_add_i32 s35, s38, 0x2000
	s_add_u32 s14, s12, 0x10000
	v_add_u32_e32 v150, s39, v136
	v_add_u32_e32 v158, s7, v136
	s_addc_u32 s15, s13, 0
	s_add_i32 s37, s7, s21
	ds_read_b128 v[138:141], v150
	ds_read_b128 v[142:145], v150 offset:1024
	ds_read_b128 v[146:149], v150 offset:2048
	ds_read_b128 v[150:153], v150 offset:3072
	ds_read_b128 v[154:157], v158
	ds_read_b128 v[162:165], v158 offset:1024
	ds_read_b128 v[168:171], v158 offset:2048
	ds_read_b128 v[172:175], v158 offset:3072
	s_add_i32 s36, s37, 0x2000
	s_add_i32 s34, 0, 0x18000
	s_add_i32 s31, 0, 0x1c000
	s_add_u32 s8, s10, 0x40000
	s_addc_u32 s9, s11, 0
	s_add_i32 s30, s34, s21
	s_add_i32 s29, s30, 0x2000
	s_add_u32 s6, s12, 0x10080
	s_addc_u32 s7, s13, 0
	s_add_i32 s40, s31, s21
	s_add_i32 s39, s40, 0x2000
	v_lshl_add_u64 v[158:159], s[16:17], 0, v[128:129]
	ds_read_b128 v[176:179], v137
	ds_read_b128 v[180:183], v137 offset:1024
	ds_read_b128 v[184:187], v137 offset:2048
	ds_read_b128 v[188:191], v137 offset:3072
	ds_read_b128 v[192:195], v137 offset:4096
	ds_read_b128 v[196:199], v137 offset:5120
	ds_read_b128 v[210:213], v137 offset:6144
	ds_read_b128 v[214:217], v137 offset:7168
	global_load_lds_dwordx4 v[158:159], off
	v_lshl_add_u64 v[158:159], s[16:17], 0, v[130:131]
	s_mov_b32 m0, s41
	s_nop 0
	global_load_lds_dwordx4 v[158:159], off
	s_waitcnt vmcnt(8)
	s_waitcnt lgkmcnt(0)
	s_barrier
	s_setprio 1
	s_waitcnt lgkmcnt(0)
	v_mfma_f32_16x16x32_bf16 v[124:127], v[138:141], v[176:179], v[124:127]
	v_mfma_f32_16x16x32_bf16 v[120:123], v[146:149], v[176:179], v[120:123]
	v_mfma_f32_16x16x32_bf16 v[116:119], v[138:141], v[184:187], v[116:119]
	v_mfma_f32_16x16x32_bf16 v[112:115], v[146:149], v[184:187], v[112:115]
	v_mfma_f32_16x16x32_bf16 v[100:103], v[138:141], v[192:195], v[100:103]
	v_mfma_f32_16x16x32_bf16 v[96:99], v[146:149], v[192:195], v[96:99]
	v_mfma_f32_16x16x32_bf16 v[84:87], v[138:141], v[210:213], v[84:87]
	v_mfma_f32_16x16x32_bf16 v[80:83], v[146:149], v[210:213], v[80:83]
	v_mfma_f32_16x16x32_bf16 v[124:127], v[142:145], v[180:183], v[124:127]
	v_mfma_f32_16x16x32_bf16 v[120:123], v[150:153], v[180:183], v[120:123]
	v_mfma_f32_16x16x32_bf16 v[116:119], v[142:145], v[188:191], v[116:119]
	v_mfma_f32_16x16x32_bf16 v[112:115], v[150:153], v[188:191], v[112:115]
	v_mfma_f32_16x16x32_bf16 v[100:103], v[142:145], v[196:199], v[100:103]
	v_mfma_f32_16x16x32_bf16 v[96:99], v[150:153], v[196:199], v[96:99]
	v_mfma_f32_16x16x32_bf16 v[84:87], v[142:145], v[214:217], v[84:87]
	v_mfma_f32_16x16x32_bf16 v[80:83], v[150:153], v[214:217], v[80:83]
	v_mfma_f32_16x16x32_bf16 v[108:111], v[154:157], v[176:179], v[108:111]
	v_mfma_f32_16x16x32_bf16 v[104:107], v[168:171], v[176:179], v[104:107]
	v_mfma_f32_16x16x32_bf16 v[92:95], v[154:157], v[184:187], v[92:95]
	v_mfma_f32_16x16x32_bf16 v[88:91], v[168:171], v[184:187], v[88:91]
	v_mfma_f32_16x16x32_bf16 v[76:79], v[154:157], v[192:195], v[76:79]
	v_mfma_f32_16x16x32_bf16 v[72:75], v[168:171], v[192:195], v[72:75]
	v_mfma_f32_16x16x32_bf16 v[68:71], v[154:157], v[210:213], v[68:71]
	v_mfma_f32_16x16x32_bf16 v[64:67], v[168:171], v[210:213], v[64:67]
	v_mfma_f32_16x16x32_bf16 v[108:111], v[162:165], v[180:183], v[108:111]
	v_mfma_f32_16x16x32_bf16 v[104:107], v[172:175], v[180:183], v[104:107]
	v_mfma_f32_16x16x32_bf16 v[92:95], v[162:165], v[188:191], v[92:95]
	v_mfma_f32_16x16x32_bf16 v[88:91], v[172:175], v[188:191], v[88:91]
	v_mfma_f32_16x16x32_bf16 v[76:79], v[162:165], v[196:199], v[76:79]
	v_mfma_f32_16x16x32_bf16 v[72:75], v[172:175], v[196:199], v[72:75]
	v_mfma_f32_16x16x32_bf16 v[68:71], v[162:165], v[214:217], v[68:71]
	v_mfma_f32_16x16x32_bf16 v[64:67], v[172:175], v[214:217], v[64:67]
	s_setprio 0
	s_barrier
	s_mov_b32 m0, s38
	v_lshl_add_u64 v[158:159], s[12:13], 0, v[160:161]
	ds_read_b128 v[176:179], v137 offset:16384
	ds_read_b128 v[180:183], v137 offset:17408
	ds_read_b128 v[184:187], v137 offset:18432
	ds_read_b128 v[188:191], v137 offset:19456
	ds_read_b128 v[192:195], v137 offset:20480
	ds_read_b128 v[196:199], v137 offset:21504
	ds_read_b128 v[210:213], v137 offset:22528
	ds_read_b128 v[214:217], v137 offset:23552
	global_load_lds_dwordx4 v[158:159], off
	v_lshl_add_u64 v[218:219], s[12:13], 0, v[132:133]
	s_mov_b32 m0, s35
	v_lshl_add_u64 v[220:221], s[14:15], 0, v[160:161]
	global_load_lds_dwordx4 v[218:219], off
	s_mov_b32 m0, s37
	v_lshl_add_u64 v[222:223], s[10:11], 0, v[130:131]
	global_load_lds_dwordx4 v[220:221], off
	v_lshl_add_u64 v[220:221], s[14:15], 0, v[132:133]
	s_mov_b32 m0, s36
	s_nop 0
	global_load_lds_dwordx4 v[220:221], off
	v_lshl_add_u64 v[220:221], s[10:11], 0, v[128:129]
	s_mov_b32 m0, s22
	s_nop 0
	global_load_lds_dwordx4 v[220:221], off
	s_mov_b32 m0, s23
	s_nop 0
	global_load_lds_dwordx4 v[222:223], off
	s_waitcnt vmcnt(8)
	s_waitcnt lgkmcnt(0)
	s_barrier
; #define PG8_STAGE(bufoff, gbase, voff) do { _Pragma("unroll") for (int _i = 0; _i < 2; ++_i) \
;         __builtin_amdgcn_global_load_lds((const unsigned*)((const char*)(gbase) + (voff)[_i]), (LAS unsigned*)(lds + (bufoff) + ldsw + _i * 8192), 16, 0, 0); } while (0)
; #define PG8_LDA(dst, b, h) do { _Pragma("unroll") for (int m = 0; m < 4; ++m) _Pragma("unroll") for (int k = 0; k < 2; ++k) dst[m][k] = *(const LAS bf16x8*)(lds + PG8_SA(b, h) + aoff + m * 2048 + k * 1024); } while (0)
; #define PG8_LDB(dst, b, h) do { _Pragma("unroll") for (int n = 0; n < 2; ++n) _Pragma("unroll") for (int k = 0; k < 2; ++k) dst[n][k] = *(const LAS bf16x8*)(lds + PG8_SB(b, h) + boff + n * 2048 + k * 1024); } while (0)
; #define PG8_MMA(ai, bj, At, Bt) do { __builtin_amdgcn_s_setprio(1); _Pragma("unroll") for (int m = 0; m < 4; ++m) _Pragma("unroll") for (int n = 0; n < 2; ++n) _Pragma("unroll") for (int k = 0; k < 2; ++k) \
;         acc[ai][bj][m][n] = __builtin_amdgcn_mfma_f32_16x16x32_bf16(Bt[n][k], At[m][k], acc[ai][bj][m][n], 0, 0, 0); __builtin_amdgcn_s_setprio(0); } while (0)
; #define PG8_WAIT_V(n) asm volatile("s_waitcnt vmcnt(" #n ")" ::: "memory")
; #define PG8_WAIT_L(n) asm volatile("s_waitcnt lgkmcnt(" #n ")" ::: "memory")
; #define PG8_BAR __builtin_amdgcn_s_barrier()
; #define PG8_SCHED __builtin_amdgcn_sched_barrier(0)
; template <class Epi, class Sched>
; DI void gemm_phase(const int wv, LAS unsigned char* lds, const int lda, const int ldb, const int K, const Sched& S, const Epi& E) {
;     ...
;             PG8_WAIT_V(8); PG8_WAIT_L(0); PG8_BAR; PG8_MMA(1, 0, At, B0); PG8_MMA(1, 1, At, B1); PG8_BAR; PG8_SCHED;
;             PG8_LDB(B0, 1, 0); PG8_LDB(B1, 1, 1); PG8_SCHED; PG8_LDA(At, 1, 0); PG8_STAGE(PG8_SA(0, 1), a2 + hstepA, voffA);
;             PG8_WAIT_V(8); PG8_WAIT_L(0); PG8_BAR; PG8_MMA(0, 0, At, B0); PG8_MMA(0, 1, At, B1); PG8_BAR; PG8_SCHED;
	s_setprio 1
	s_waitcnt lgkmcnt(0)
	v_mfma_f32_16x16x32_bf16 v[60:63], v[138:141], v[176:179], v[60:63]
	v_mfma_f32_16x16x32_bf16 v[56:59], v[146:149], v[176:179], v[56:59]
	v_mfma_f32_16x16x32_bf16 v[52:55], v[138:141], v[184:187], v[52:55]
	v_mfma_f32_16x16x32_bf16 v[48:51], v[146:149], v[184:187], v[48:51]
	v_mfma_f32_16x16x32_bf16 v[36:39], v[138:141], v[192:195], v[36:39]
	v_mfma_f32_16x16x32_bf16 v[32:35], v[146:149], v[192:195], v[32:35]
	v_mfma_f32_16x16x32_bf16 v[20:23], v[138:141], v[210:213], v[20:23]
	v_mfma_f32_16x16x32_bf16 v[16:19], v[146:149], v[210:213], v[16:19]
	v_mfma_f32_16x16x32_bf16 v[60:63], v[142:145], v[180:183], v[60:63]
	v_mfma_f32_16x16x32_bf16 v[56:59], v[150:153], v[180:183], v[56:59]
	v_mfma_f32_16x16x32_bf16 v[52:55], v[142:145], v[188:191], v[52:55]
	v_mfma_f32_16x16x32_bf16 v[48:51], v[150:153], v[188:191], v[48:51]
	v_mfma_f32_16x16x32_bf16 v[36:39], v[142:145], v[196:199], v[36:39]
	v_mfma_f32_16x16x32_bf16 v[32:35], v[150:153], v[196:199], v[32:35]
	v_mfma_f32_16x16x32_bf16 v[20:23], v[142:145], v[214:217], v[20:23]
	v_mfma_f32_16x16x32_bf16 v[16:19], v[150:153], v[214:217], v[16:19]
	v_mfma_f32_16x16x32_bf16 v[44:47], v[154:157], v[176:179], v[44:47]
	v_mfma_f32_16x16x32_bf16 v[40:43], v[168:171], v[176:179], v[40:43]
	v_mfma_f32_16x16x32_bf16 v[28:31], v[154:157], v[184:187], v[28:31]
	v_mfma_f32_16x16x32_bf16 v[24:27], v[168:171], v[184:187], v[24:27]
	v_mfma_f32_16x16x32_bf16 v[12:15], v[154:157], v[192:195], v[12:15]
	v_mfma_f32_16x16x32_bf16 v[8:11], v[168:171], v[192:195], v[8:11]
	v_mfma_f32_16x16x32_bf16 v[4:7], v[154:157], v[210:213], v[4:7]
	v_mfma_f32_16x16x32_bf16 v[0:3], v[168:171], v[210:213], v[0:3]
	v_mfma_f32_16x16x32_bf16 v[44:47], v[162:165], v[180:183], v[44:47]
	v_mfma_f32_16x16x32_bf16 v[40:43], v[172:175], v[180:183], v[40:43]
	v_mfma_f32_16x16x32_bf16 v[28:31], v[162:165], v[188:191], v[28:31]
	v_mfma_f32_16x16x32_bf16 v[24:27], v[172:175], v[188:191], v[24:27]
	v_mfma_f32_16x16x32_bf16 v[12:15], v[162:165], v[196:199], v[12:15]
	v_mfma_f32_16x16x32_bf16 v[8:11], v[172:175], v[196:199], v[8:11]
	v_mfma_f32_16x16x32_bf16 v[4:7], v[162:165], v[214:217], v[4:7]
	v_mfma_f32_16x16x32_bf16 v[0:3], v[172:175], v[214:217], v[0:3]
	s_setprio 0
	s_barrier
	v_add_u32_e32 v150, s34, v136
	v_add_u32_e32 v172, s31, v136
	ds_read_b128 v[138:141], v150
	ds_read_b128 v[142:145], v150 offset:1024
	ds_read_b128 v[146:149], v150 offset:2048
	ds_read_b128 v[150:153], v150 offset:3072
	ds_read_b128 v[154:157], v172
	ds_read_b128 v[162:165], v172 offset:1024
	ds_read_b128 v[168:171], v172 offset:2048
	ds_read_b128 v[172:175], v172 offset:3072
	s_mov_b32 m0, s24
	v_lshl_add_u64 v[224:225], s[8:9], 0, v[128:129]
	ds_read_b128 v[176:179], v137 offset:32768
	ds_read_b128 v[180:183], v137 offset:33792
	ds_read_b128 v[184:187], v137 offset:34816
	ds_read_b128 v[188:191], v137 offset:35840
	ds_read_b128 v[192:195], v137 offset:36864
	ds_read_b128 v[196:199], v137 offset:37888
	ds_read_b128 v[210:213], v137 offset:38912
	ds_read_b128 v[214:217], v137 offset:39936
	global_load_lds_dwordx4 v[224:225], off
	v_lshl_add_u64 v[224:225], s[8:9], 0, v[130:131]
	s_mov_b32 m0, s25
	s_nop 0
	global_load_lds_dwordx4 v[224:225], off
	s_waitcnt vmcnt(8)
	s_waitcnt lgkmcnt(0)
	s_barrier
	s_setprio 1
	s_waitcnt lgkmcnt(0)
	v_mfma_f32_16x16x32_bf16 v[124:127], v[138:141], v[176:179], v[124:127]
	v_mfma_f32_16x16x32_bf16 v[120:123], v[146:149], v[176:179], v[120:123]
	v_mfma_f32_16x16x32_bf16 v[116:119], v[138:141], v[184:187], v[116:119]
	v_mfma_f32_16x16x32_bf16 v[112:115], v[146:149], v[184:187], v[112:115]
	v_mfma_f32_16x16x32_bf16 v[100:103], v[138:141], v[192:195], v[100:103]
	v_mfma_f32_16x16x32_bf16 v[96:99], v[146:149], v[192:195], v[96:99]
	v_mfma_f32_16x16x32_bf16 v[84:87], v[138:141], v[210:213], v[84:87]
	v_mfma_f32_16x16x32_bf16 v[80:83], v[146:149], v[210:213], v[80:83]
	v_mfma_f32_16x16x32_bf16 v[124:127], v[142:145], v[180:183], v[124:127]
	v_mfma_f32_16x16x32_bf16 v[120:123], v[150:153], v[180:183], v[120:123]
	v_mfma_f32_16x16x32_bf16 v[116:119], v[142:145], v[188:191], v[116:119]
	v_mfma_f32_16x16x32_bf16 v[112:115], v[150:153], v[188:191], v[112:115]
	v_mfma_f32_16x16x32_bf16 v[100:103], v[142:145], v[196:199], v[100:103]
	v_mfma_f32_16x16x32_bf16 v[96:99], v[150:153], v[196:199], v[96:99]
	v_mfma_f32_16x16x32_bf16 v[84:87], v[142:145], v[214:217], v[84:87]
	v_mfma_f32_16x16x32_bf16 v[80:83], v[150:153], v[214:217], v[80:83]
	v_mfma_f32_16x16x32_bf16 v[108:111], v[154:157], v[176:179], v[108:111]
	v_mfma_f32_16x16x32_bf16 v[104:107], v[168:171], v[176:179], v[104:107]
	v_mfma_f32_16x16x32_bf16 v[92:95], v[154:157], v[184:187], v[92:95]
	v_mfma_f32_16x16x32_bf16 v[88:91], v[168:171], v[184:187], v[88:91]
	v_mfma_f32_16x16x32_bf16 v[76:79], v[154:157], v[192:195], v[76:79]
	v_mfma_f32_16x16x32_bf16 v[72:75], v[168:171], v[192:195], v[72:75]
	v_mfma_f32_16x16x32_bf16 v[68:71], v[154:157], v[210:213], v[68:71]
	v_mfma_f32_16x16x32_bf16 v[64:67], v[168:171], v[210:213], v[64:67]
	v_mfma_f32_16x16x32_bf16 v[108:111], v[162:165], v[180:183], v[108:111]
	v_mfma_f32_16x16x32_bf16 v[104:107], v[172:175], v[180:183], v[104:107]
	v_mfma_f32_16x16x32_bf16 v[92:95], v[162:165], v[188:191], v[92:95]
	v_mfma_f32_16x16x32_bf16 v[88:91], v[172:175], v[188:191], v[88:91]
	v_mfma_f32_16x16x32_bf16 v[76:79], v[162:165], v[196:199], v[76:79]
	v_mfma_f32_16x16x32_bf16 v[72:75], v[172:175], v[196:199], v[72:75]
	v_mfma_f32_16x16x32_bf16 v[68:71], v[162:165], v[214:217], v[68:71]
	v_mfma_f32_16x16x32_bf16 v[64:67], v[172:175], v[214:217], v[64:67]
	s_setprio 0
	s_barrier
; #define PG8_STAGE(bufoff, gbase, voff) do { _Pragma("unroll") for (int _i = 0; _i < 2; ++_i) \
;         __builtin_amdgcn_global_load_lds((const unsigned*)((const char*)(gbase) + (voff)[_i]), (LAS unsigned*)(lds + (bufoff) + ldsw + _i * 8192), 16, 0, 0); } while (0)
; #define PG8_LDA(dst, b, h) do { _Pragma("unroll") for (int m = 0; m < 4; ++m) _Pragma("unroll") for (int k = 0; k < 2; ++k) dst[m][k] = *(const LAS bf16x8*)(lds + PG8_SA(b, h) + aoff + m * 2048 + k * 1024); } while (0)
; #define PG8_MMA(ai, bj, At, Bt) do { __builtin_amdgcn_s_setprio(1); _Pragma("unroll") for (int m = 0; m < 4; ++m) _Pragma("unroll") for (int n = 0; n < 2; ++n) _Pragma("unroll") for (int k = 0; k < 2; ++k) \
;         acc[ai][bj][m][n] = __builtin_amdgcn_mfma_f32_16x16x32_bf16(Bt[n][k], At[m][k], acc[ai][bj][m][n], 0, 0, 0); __builtin_amdgcn_s_setprio(0); } while (0)
; #define PG8_WAIT_V(n) asm volatile("s_waitcnt vmcnt(" #n ")" ::: "memory")
; #define PG8_WAIT_L(n) asm volatile("s_waitcnt lgkmcnt(" #n ")" ::: "memory")
; #define PG8_BAR __builtin_amdgcn_s_barrier()
; #define PG8_SCHED __builtin_amdgcn_sched_barrier(0)
; template <class Epi, class Sched>
; DI void gemm_phase(const int wv, LAS unsigned char* lds, const int lda, const int ldb, const int K, const Sched& S, const Epi& E) {
;     ...
;             PG8_LDA(At, 1, 1); PG8_STAGE(PG8_SB(1, 0), b3, voffB); PG8_STAGE(PG8_SB(1, 1), b3 + hstepB, voffB); PG8_STAGE(PG8_SA(1, 0), a3, voffA);
;             PG8_WAIT_V(8); PG8_WAIT_L(0); PG8_BAR; PG8_MMA(1, 0, At, B0); PG8_MMA(1, 1, At, B1); PG8_BAR; PG8_SCHED;
;         }
;         if (wr == 0) PG8_BAR;
	s_mov_b32 m0, s30
	v_lshl_add_u64 v[158:159], v[158:159], 0, s[78:79]
	ds_read_b128 v[176:179], v137 offset:49152
	ds_read_b128 v[180:183], v137 offset:50176
	ds_read_b128 v[184:187], v137 offset:51200
	ds_read_b128 v[188:191], v137 offset:52224
	ds_read_b128 v[192:195], v137 offset:53248
	ds_read_b128 v[196:199], v137 offset:54272
	ds_read_b128 v[210:213], v137 offset:55296
	ds_read_b128 v[214:217], v137 offset:56320
	global_load_lds_dwordx4 v[158:159], off
	v_lshl_add_u64 v[158:159], v[218:219], 0, s[78:79]
	s_mov_b32 m0, s29
	s_nop 0
	global_load_lds_dwordx4 v[158:159], off
	v_lshl_add_u64 v[158:159], s[6:7], 0, v[160:161]
	s_mov_b32 m0, s40
	s_nop 0
	global_load_lds_dwordx4 v[158:159], off
	v_lshl_add_u64 v[158:159], s[6:7], 0, v[132:133]
	s_mov_b32 m0, s39
	s_nop 0
	global_load_lds_dwordx4 v[158:159], off
	v_lshl_add_u64 v[158:159], v[220:221], 0, s[78:79]
	s_mov_b32 m0, s27
	s_nop 0
	global_load_lds_dwordx4 v[158:159], off
	v_lshl_add_u64 v[158:159], v[222:223], 0, s[78:79]
	s_mov_b32 m0, s28
	s_nop 0
	global_load_lds_dwordx4 v[158:159], off
	s_waitcnt vmcnt(8)
	s_waitcnt lgkmcnt(0)
	s_barrier
	s_setprio 1
	s_waitcnt lgkmcnt(0)
	v_mfma_f32_16x16x32_bf16 v[60:63], v[138:141], v[176:179], v[60:63]
	v_mfma_f32_16x16x32_bf16 v[56:59], v[146:149], v[176:179], v[56:59]
	v_mfma_f32_16x16x32_bf16 v[52:55], v[138:141], v[184:187], v[52:55]
	v_mfma_f32_16x16x32_bf16 v[48:51], v[146:149], v[184:187], v[48:51]
	v_mfma_f32_16x16x32_bf16 v[36:39], v[138:141], v[192:195], v[36:39]
	v_mfma_f32_16x16x32_bf16 v[32:35], v[146:149], v[192:195], v[32:35]
	v_mfma_f32_16x16x32_bf16 v[20:23], v[138:141], v[210:213], v[20:23]
	v_mfma_f32_16x16x32_bf16 v[16:19], v[146:149], v[210:213], v[16:19]
	v_mfma_f32_16x16x32_bf16 v[60:63], v[142:145], v[180:183], v[60:63]
	v_mfma_f32_16x16x32_bf16 v[56:59], v[150:153], v[180:183], v[56:59]
	v_mfma_f32_16x16x32_bf16 v[52:55], v[142:145], v[188:191], v[52:55]
	v_mfma_f32_16x16x32_bf16 v[48:51], v[150:153], v[188:191], v[48:51]
	v_mfma_f32_16x16x32_bf16 v[36:39], v[142:145], v[196:199], v[36:39]
	v_mfma_f32_16x16x32_bf16 v[32:35], v[150:153], v[196:199], v[32:35]
	v_mfma_f32_16x16x32_bf16 v[20:23], v[142:145], v[214:217], v[20:23]
	v_mfma_f32_16x16x32_bf16 v[16:19], v[150:153], v[214:217], v[16:19]
	v_mfma_f32_16x16x32_bf16 v[44:47], v[154:157], v[176:179], v[44:47]
	v_mfma_f32_16x16x32_bf16 v[40:43], v[168:171], v[176:179], v[40:43]
	v_mfma_f32_16x16x32_bf16 v[28:31], v[154:157], v[184:187], v[28:31]
	v_mfma_f32_16x16x32_bf16 v[24:27], v[168:171], v[184:187], v[24:27]
	v_mfma_f32_16x16x32_bf16 v[12:15], v[154:157], v[192:195], v[12:15]
	v_mfma_f32_16x16x32_bf16 v[8:11], v[168:171], v[192:195], v[8:11]
	v_mfma_f32_16x16x32_bf16 v[4:7], v[154:157], v[210:213], v[4:7]
	v_mfma_f32_16x16x32_bf16 v[0:3], v[168:171], v[210:213], v[0:3]
	v_mfma_f32_16x16x32_bf16 v[44:47], v[162:165], v[180:183], v[44:47]
	v_mfma_f32_16x16x32_bf16 v[40:43], v[172:175], v[180:183], v[40:43]
	v_mfma_f32_16x16x32_bf16 v[28:31], v[162:165], v[188:191], v[28:31]
	v_mfma_f32_16x16x32_bf16 v[24:27], v[172:175], v[188:191], v[24:27]
	v_mfma_f32_16x16x32_bf16 v[12:15], v[162:165], v[196:199], v[12:15]
	v_mfma_f32_16x16x32_bf16 v[8:11], v[172:175], v[196:199], v[8:11]
	v_mfma_f32_16x16x32_bf16 v[4:7], v[162:165], v[214:217], v[4:7]
	v_mfma_f32_16x16x32_bf16 v[0:3], v[172:175], v[214:217], v[0:3]
	s_setprio 0
	s_barrier
	s_andn2_b64 vcc, exec, s[4:5]
	s_mov_b64 s[6:7], -1
	s_mov_b64 s[4:5], 0
	s_mov_b64 s[8:9], 0x100
	s_cbranch_vccz .LBB0_516
	s_cmpk_lt_u32 s20, 0x100
	s_cbranch_scc0 .LBB0_519
	s_barrier

; #define PG8_STAGE(bufoff, gbase, voff) do { _Pragma("unroll") for (int _i = 0; _i < 2; ++_i) \
;         __builtin_amdgcn_global_load_lds((const unsigned*)((const char*)(gbase) + (voff)[_i]), (LAS unsigned*)(lds + (bufoff) + ldsw + _i * 8192), 16, 0, 0); } while (0)
; #define PG8_LDA(dst, b, h) do { _Pragma("unroll") for (int m = 0; m < 4; ++m) _Pragma("unroll") for (int k = 0; k < 2; ++k) dst[m][k] = *(const LAS bf16x8*)(lds + PG8_SA(b, h) + aoff + m * 2048 + k * 1024); } while (0)
; #define PG8_LDB(dst, b, h) do { _Pragma("unroll") for (int n = 0; n < 2; ++n) _Pragma("unroll") for (int k = 0; k < 2; ++k) dst[n][k] = *(const LAS bf16x8*)(lds + PG8_SB(b, h) + boff + n * 2048 + k * 1024); } while (0)
; #define PG8_MMA(ai, bj, At, Bt) do { __builtin_amdgcn_s_setprio(1); _Pragma("unroll") for (int m = 0; m < 4; ++m) _Pragma("unroll") for (int n = 0; n < 2; ++n) _Pragma("unroll") for (int k = 0; k < 2; ++k) \
;         acc[ai][bj][m][n] = __builtin_amdgcn_mfma_f32_16x16x32_bf16(Bt[n][k], At[m][k], acc[ai][bj][m][n], 0, 0, 0); __builtin_amdgcn_s_setprio(0); } while (0)
; #define PG8_WAIT_V(n) asm volatile("s_waitcnt vmcnt(" #n ")" ::: "memory")
; #define PG8_WAIT_L(n) asm volatile("s_waitcnt lgkmcnt(" #n ")" ::: "memory")
; #define PG8_BAR __builtin_amdgcn_s_barrier()
; #define PG8_SCHED __builtin_amdgcn_sched_barrier(0)
; template <class Epi, class Sched>
; DI void gemm_phase(const int wv, LAS unsigned char* lds, const int lda, const int ldb, const int K, const Sched& S, const Epi& E) {
;     ...
;             const char* a1 = cA + (size_t)(t + 1) * kstep;
;             const char* a2 = last ? nA : cA + (size_t)(t + 2) * kstep; const char* b2 = last ? nB : cB + (size_t)(t + 2) * kstep;
;             const char* a3 = a2 + kstep; const char* b3 = b2 + kstep;
;             PG8_LDB(B0, 0, 0); PG8_LDB(B1, 0, 1); PG8_SCHED; PG8_LDA(At, 0, 0); PG8_STAGE(PG8_SA(1, 1), a1 + hstepA, voffA);
;             PG8_WAIT_V(8); PG8_WAIT_L(0); PG8_BAR; PG8_MMA(0, 0, At, B0); PG8_MMA(0, 1, At, B1); PG8_BAR; PG8_SCHED;
;             PG8_LDA(At, 0, 1); PG8_STAGE(PG8_SB(0, 0), b2, voffB); PG8_STAGE(PG8_SB(0, 1), b2 + hstepB, voffB); PG8_STAGE(PG8_SA(0, 0), a2, voffA);
;             PG8_WAIT_V(8); PG8_WAIT_L(0); PG8_BAR; PG8_MMA(1, 0, At, B0); PG8_MMA(1, 1, At, B1); PG8_BAR; PG8_SCHED;
.LBB0_686:
	s_add_u32 s18, s16, 0xfff80080
	s_addc_u32 s19, s17, -1
	s_add_i32 s42, 0, 0x10000
	s_cmp_eq_u32 s41, 28
	s_cselect_b32 s21, s13, s19
	s_cselect_b32 s20, s12, s18
	s_cselect_b32 s19, s15, s40
	s_cselect_b32 s18, s14, s11
	s_add_i32 s44, 0, 0x14000
	v_add_u32_e32 v140, s42, v157
	v_add_u32_e32 v154, s44, v157
	ds_read_b128 v[128:131], v140
	ds_read_b128 v[132:135], v140 offset:1024
	ds_read_b128 v[136:139], v140 offset:2048
	ds_read_b128 v[140:143], v140 offset:3072
	ds_read_b128 v[162:165], v154
	ds_read_b128 v[168:171], v154 offset:1024
	ds_read_b128 v[172:175], v154 offset:2048
	ds_read_b128 v[176:179], v154 offset:3072
	v_lshl_add_u64 v[154:155], s[16:17], 0, v[152:153]
	s_add_i32 m0, s27, 0xc000
	ds_read_b128 v[180:183], v159
	ds_read_b128 v[184:187], v159 offset:1024
	ds_read_b128 v[188:191], v159 offset:2048
	ds_read_b128 v[192:195], v159 offset:3072
	ds_read_b128 v[196:199], v159 offset:4096
	ds_read_b128 v[210:213], v159 offset:5120
	ds_read_b128 v[214:217], v159 offset:6144
	ds_read_b128 v[218:221], v159 offset:7168
	global_load_lds_dwordx4 v[154:155], off
	v_lshl_add_u64 v[154:155], s[16:17], 0, v[150:151]
	s_add_i32 m0, s27, 0xe000
	s_nop 0
	global_load_lds_dwordx4 v[154:155], off
	s_waitcnt vmcnt(8)
	s_waitcnt lgkmcnt(0)
	s_barrier
	s_setprio 1
	s_waitcnt lgkmcnt(0)
	v_mfma_f32_16x16x32_bf16 v[124:127], v[128:131], v[180:183], v[124:127]
	v_mfma_f32_16x16x32_bf16 v[120:123], v[136:139], v[180:183], v[120:123]
	v_mfma_f32_16x16x32_bf16 v[116:119], v[128:131], v[188:191], v[116:119]
	v_mfma_f32_16x16x32_bf16 v[108:111], v[136:139], v[188:191], v[108:111]
	v_mfma_f32_16x16x32_bf16 v[100:103], v[128:131], v[196:199], v[100:103]
	v_mfma_f32_16x16x32_bf16 v[92:95], v[136:139], v[196:199], v[92:95]
	v_mfma_f32_16x16x32_bf16 v[84:87], v[128:131], v[214:217], v[84:87]
	v_mfma_f32_16x16x32_bf16 v[76:79], v[136:139], v[214:217], v[76:79]
	v_mfma_f32_16x16x32_bf16 v[124:127], v[132:135], v[184:187], v[124:127]
	v_mfma_f32_16x16x32_bf16 v[120:123], v[140:143], v[184:187], v[120:123]
	v_mfma_f32_16x16x32_bf16 v[116:119], v[132:135], v[192:195], v[116:119]
	v_mfma_f32_16x16x32_bf16 v[108:111], v[140:143], v[192:195], v[108:111]
	v_mfma_f32_16x16x32_bf16 v[100:103], v[132:135], v[210:213], v[100:103]
	v_mfma_f32_16x16x32_bf16 v[92:95], v[140:143], v[210:213], v[92:95]
	v_mfma_f32_16x16x32_bf16 v[84:87], v[132:135], v[218:221], v[84:87]
	v_mfma_f32_16x16x32_bf16 v[76:79], v[140:143], v[218:221], v[76:79]
	v_mfma_f32_16x16x32_bf16 v[112:115], v[162:165], v[180:183], v[112:115]
	v_mfma_f32_16x16x32_bf16 v[104:107], v[172:175], v[180:183], v[104:107]
	v_mfma_f32_16x16x32_bf16 v[96:99], v[162:165], v[188:191], v[96:99]
	v_mfma_f32_16x16x32_bf16 v[88:91], v[172:175], v[188:191], v[88:91]
	v_mfma_f32_16x16x32_bf16 v[80:83], v[162:165], v[196:199], v[80:83]
	v_mfma_f32_16x16x32_bf16 v[72:75], v[172:175], v[196:199], v[72:75]
	v_mfma_f32_16x16x32_bf16 v[68:71], v[162:165], v[214:217], v[68:71]
	v_mfma_f32_16x16x32_bf16 v[64:67], v[172:175], v[214:217], v[64:67]
	v_mfma_f32_16x16x32_bf16 v[112:115], v[168:171], v[184:187], v[112:115]
	v_mfma_f32_16x16x32_bf16 v[104:107], v[176:179], v[184:187], v[104:107]
	v_mfma_f32_16x16x32_bf16 v[96:99], v[168:171], v[192:195], v[96:99]
	v_mfma_f32_16x16x32_bf16 v[88:91], v[176:179], v[192:195], v[88:91]
	v_mfma_f32_16x16x32_bf16 v[80:83], v[168:171], v[210:213], v[80:83]
	v_mfma_f32_16x16x32_bf16 v[72:75], v[176:179], v[210:213], v[72:75]
	v_mfma_f32_16x16x32_bf16 v[68:71], v[168:171], v[218:221], v[68:71]
	v_mfma_f32_16x16x32_bf16 v[64:67], v[176:179], v[218:221], v[64:67]
	s_setprio 0
	s_barrier
	s_add_i32 s42, s42, s26
	v_lshl_add_u64 v[154:155], s[18:19], 0, v[160:161]
	s_mov_b32 m0, s42
	ds_read_b128 v[180:183], v159 offset:16384
	ds_read_b128 v[184:187], v159 offset:17408
	ds_read_b128 v[188:191], v159 offset:18432
	ds_read_b128 v[192:195], v159 offset:19456
	ds_read_b128 v[196:199], v159 offset:20480
	ds_read_b128 v[210:213], v159 offset:21504
	ds_read_b128 v[214:217], v159 offset:22528
	ds_read_b128 v[218:221], v159 offset:23552
	global_load_lds_dwordx4 v[154:155], off
	s_add_i32 m0, s42, 0x2000
	s_add_u32 s42, s18, 0x80000
	v_lshl_add_u64 v[222:223], s[18:19], 0, v[144:145]
	s_addc_u32 s43, s19, 0
	s_add_i32 s44, s44, s26
	global_load_lds_dwordx4 v[222:223], off
	v_lshl_add_u64 v[224:225], s[42:43], 0, v[160:161]
	s_mov_b32 m0, s44
	v_lshl_add_u64 v[226:227], s[20:21], 0, v[146:147]
	global_load_lds_dwordx4 v[224:225], off
	v_lshl_add_u64 v[224:225], s[42:43], 0, v[144:145]
	s_add_i32 m0, s44, 0x2000
	s_nop 0
	global_load_lds_dwordx4 v[224:225], off
	v_lshl_add_u64 v[224:225], s[20:21], 0, v[148:149]
	s_mov_b32 m0, s27
	s_nop 0
	global_load_lds_dwordx4 v[224:225], off
	s_mov_b32 m0, s28
	s_nop 0
	global_load_lds_dwordx4 v[226:227], off
	s_waitcnt vmcnt(8)
	s_waitcnt lgkmcnt(0)
	s_barrier
; #define PG8_STAGE(bufoff, gbase, voff) do { _Pragma("unroll") for (int _i = 0; _i < 2; ++_i) \
;         __builtin_amdgcn_global_load_lds((const unsigned*)((const char*)(gbase) + (voff)[_i]), (LAS unsigned*)(lds + (bufoff) + ldsw + _i * 8192), 16, 0, 0); } while (0)
; #define PG8_LDA(dst, b, h) do { _Pragma("unroll") for (int m = 0; m < 4; ++m) _Pragma("unroll") for (int k = 0; k < 2; ++k) dst[m][k] = *(const LAS bf16x8*)(lds + PG8_SA(b, h) + aoff + m * 2048 + k * 1024); } while (0)
; #define PG8_LDB(dst, b, h) do { _Pragma("unroll") for (int n = 0; n < 2; ++n) _Pragma("unroll") for (int k = 0; k < 2; ++k) dst[n][k] = *(const LAS bf16x8*)(lds + PG8_SB(b, h) + boff + n * 2048 + k * 1024); } while (0)
; #define PG8_MMA(ai, bj, At, Bt) do { __builtin_amdgcn_s_setprio(1); _Pragma("unroll") for (int m = 0; m < 4; ++m) _Pragma("unroll") for (int n = 0; n < 2; ++n) _Pragma("unroll") for (int k = 0; k < 2; ++k) \
;         acc[ai][bj][m][n] = __builtin_amdgcn_mfma_f32_16x16x32_bf16(Bt[n][k], At[m][k], acc[ai][bj][m][n], 0, 0, 0); __builtin_amdgcn_s_setprio(0); } while (0)
; #define PG8_WAIT_V(n) asm volatile("s_waitcnt vmcnt(" #n ")" ::: "memory")
; #define PG8_WAIT_L(n) asm volatile("s_waitcnt lgkmcnt(" #n ")" ::: "memory")
; #define PG8_BAR __builtin_amdgcn_s_barrier()
; #define PG8_SCHED __builtin_amdgcn_sched_barrier(0)
; template <class Epi, class Sched>
; DI void gemm_phase(const int wv, LAS unsigned char* lds, const int lda, const int ldb, const int K, const Sched& S, const Epi& E) {
;     ...
;             PG8_WAIT_V(8); PG8_WAIT_L(0); PG8_BAR; PG8_MMA(1, 0, At, B0); PG8_MMA(1, 1, At, B1); PG8_BAR; PG8_SCHED;
;             PG8_LDB(B0, 1, 0); PG8_LDB(B1, 1, 1); PG8_SCHED; PG8_LDA(At, 1, 0); PG8_STAGE(PG8_SA(0, 1), a2 + hstepA, voffA);
;             PG8_WAIT_V(8); PG8_WAIT_L(0); PG8_BAR; PG8_MMA(0, 0, At, B0); PG8_MMA(0, 1, At, B1); PG8_BAR; PG8_SCHED;
	s_setprio 1
	s_waitcnt lgkmcnt(0)
	v_mfma_f32_16x16x32_bf16 v[60:63], v[128:131], v[180:183], v[60:63]
	v_mfma_f32_16x16x32_bf16 v[56:59], v[136:139], v[180:183], v[56:59]
	v_mfma_f32_16x16x32_bf16 v[52:55], v[128:131], v[188:191], v[52:55]
	v_mfma_f32_16x16x32_bf16 v[44:47], v[136:139], v[188:191], v[44:47]
	v_mfma_f32_16x16x32_bf16 v[36:39], v[128:131], v[196:199], v[36:39]
	v_mfma_f32_16x16x32_bf16 v[28:31], v[136:139], v[196:199], v[28:31]
	v_mfma_f32_16x16x32_bf16 v[20:23], v[128:131], v[214:217], v[20:23]
	v_mfma_f32_16x16x32_bf16 v[12:15], v[136:139], v[214:217], v[12:15]
	v_mfma_f32_16x16x32_bf16 v[60:63], v[132:135], v[184:187], v[60:63]
	v_mfma_f32_16x16x32_bf16 v[56:59], v[140:143], v[184:187], v[56:59]
	v_mfma_f32_16x16x32_bf16 v[52:55], v[132:135], v[192:195], v[52:55]
	v_mfma_f32_16x16x32_bf16 v[44:47], v[140:143], v[192:195], v[44:47]
	v_mfma_f32_16x16x32_bf16 v[36:39], v[132:135], v[210:213], v[36:39]
	v_mfma_f32_16x16x32_bf16 v[28:31], v[140:143], v[210:213], v[28:31]
	v_mfma_f32_16x16x32_bf16 v[20:23], v[132:135], v[218:221], v[20:23]
	v_mfma_f32_16x16x32_bf16 v[12:15], v[140:143], v[218:221], v[12:15]
	v_mfma_f32_16x16x32_bf16 v[48:51], v[162:165], v[180:183], v[48:51]
	v_mfma_f32_16x16x32_bf16 v[40:43], v[172:175], v[180:183], v[40:43]
	v_mfma_f32_16x16x32_bf16 v[32:35], v[162:165], v[188:191], v[32:35]
	v_mfma_f32_16x16x32_bf16 v[24:27], v[172:175], v[188:191], v[24:27]
	v_mfma_f32_16x16x32_bf16 v[16:19], v[162:165], v[196:199], v[16:19]
	v_mfma_f32_16x16x32_bf16 v[8:11], v[172:175], v[196:199], v[8:11]
	v_mfma_f32_16x16x32_bf16 v[4:7], v[162:165], v[214:217], v[4:7]
	v_mfma_f32_16x16x32_bf16 v[0:3], v[172:175], v[214:217], v[0:3]
	v_mfma_f32_16x16x32_bf16 v[48:51], v[168:171], v[184:187], v[48:51]
	v_mfma_f32_16x16x32_bf16 v[40:43], v[176:179], v[184:187], v[40:43]
	v_mfma_f32_16x16x32_bf16 v[32:35], v[168:171], v[192:195], v[32:35]
	v_mfma_f32_16x16x32_bf16 v[24:27], v[176:179], v[192:195], v[24:27]
	v_mfma_f32_16x16x32_bf16 v[16:19], v[168:171], v[210:213], v[16:19]
	v_mfma_f32_16x16x32_bf16 v[8:11], v[176:179], v[210:213], v[8:11]
	v_mfma_f32_16x16x32_bf16 v[4:7], v[168:171], v[218:221], v[4:7]
	v_mfma_f32_16x16x32_bf16 v[0:3], v[176:179], v[218:221], v[0:3]
	s_setprio 0
	s_barrier
	s_add_i32 s42, 0, 0x18000
	s_add_i32 s43, 0, 0x1c000
	v_add_u32_e32 v140, s42, v157
	v_add_u32_e32 v176, s43, v157
	ds_read_b128 v[128:131], v140
	ds_read_b128 v[132:135], v140 offset:1024
	ds_read_b128 v[136:139], v140 offset:2048
	ds_read_b128 v[140:143], v140 offset:3072
	ds_read_b128 v[162:165], v176
	ds_read_b128 v[168:171], v176 offset:1024
	ds_read_b128 v[172:175], v176 offset:2048
	ds_read_b128 v[176:179], v176 offset:3072
	s_add_u32 s20, s20, 0x80000
	s_addc_u32 s21, s21, 0
	s_mov_b32 m0, s29
	v_lshl_add_u64 v[228:229], s[20:21], 0, v[148:149]
	ds_read_b128 v[180:183], v159 offset:32768
	ds_read_b128 v[184:187], v159 offset:33792
	ds_read_b128 v[188:191], v159 offset:34816
	ds_read_b128 v[192:195], v159 offset:35840
	ds_read_b128 v[196:199], v159 offset:36864
	ds_read_b128 v[210:213], v159 offset:37888
	ds_read_b128 v[214:217], v159 offset:38912
	ds_read_b128 v[218:221], v159 offset:39936
	global_load_lds_dwordx4 v[228:229], off
	v_lshl_add_u64 v[228:229], s[20:21], 0, v[146:147]
	s_mov_b32 m0, s30
	s_nop 0
	global_load_lds_dwordx4 v[228:229], off
	s_waitcnt vmcnt(8)
	s_waitcnt lgkmcnt(0)
	s_barrier
	s_setprio 1
	s_waitcnt lgkmcnt(0)
	v_mfma_f32_16x16x32_bf16 v[124:127], v[128:131], v[180:183], v[124:127]
	v_mfma_f32_16x16x32_bf16 v[120:123], v[136:139], v[180:183], v[120:123]
	v_mfma_f32_16x16x32_bf16 v[116:119], v[128:131], v[188:191], v[116:119]
	v_mfma_f32_16x16x32_bf16 v[108:111], v[136:139], v[188:191], v[108:111]
	v_mfma_f32_16x16x32_bf16 v[100:103], v[128:131], v[196:199], v[100:103]
	v_mfma_f32_16x16x32_bf16 v[92:95], v[136:139], v[196:199], v[92:95]
	v_mfma_f32_16x16x32_bf16 v[84:87], v[128:131], v[214:217], v[84:87]
	v_mfma_f32_16x16x32_bf16 v[76:79], v[136:139], v[214:217], v[76:79]
	v_mfma_f32_16x16x32_bf16 v[124:127], v[132:135], v[184:187], v[124:127]
	v_mfma_f32_16x16x32_bf16 v[120:123], v[140:143], v[184:187], v[120:123]
	v_mfma_f32_16x16x32_bf16 v[116:119], v[132:135], v[192:195], v[116:119]
	v_mfma_f32_16x16x32_bf16 v[108:111], v[140:143], v[192:195], v[108:111]
	v_mfma_f32_16x16x32_bf16 v[100:103], v[132:135], v[210:213], v[100:103]
	v_mfma_f32_16x16x32_bf16 v[92:95], v[140:143], v[210:213], v[92:95]
	v_mfma_f32_16x16x32_bf16 v[84:87], v[132:135], v[218:221], v[84:87]
	v_mfma_f32_16x16x32_bf16 v[76:79], v[140:143], v[218:221], v[76:79]
	v_mfma_f32_16x16x32_bf16 v[112:115], v[162:165], v[180:183], v[112:115]
	v_mfma_f32_16x16x32_bf16 v[104:107], v[172:175], v[180:183], v[104:107]
	v_mfma_f32_16x16x32_bf16 v[96:99], v[162:165], v[188:191], v[96:99]
	v_mfma_f32_16x16x32_bf16 v[88:91], v[172:175], v[188:191], v[88:91]
	v_mfma_f32_16x16x32_bf16 v[80:83], v[162:165], v[196:199], v[80:83]
	v_mfma_f32_16x16x32_bf16 v[72:75], v[172:175], v[196:199], v[72:75]
	v_mfma_f32_16x16x32_bf16 v[68:71], v[162:165], v[214:217], v[68:71]
	v_mfma_f32_16x16x32_bf16 v[64:67], v[172:175], v[214:217], v[64:67]
	v_mfma_f32_16x16x32_bf16 v[112:115], v[168:171], v[184:187], v[112:115]
	v_mfma_f32_16x16x32_bf16 v[104:107], v[176:179], v[184:187], v[104:107]
	v_mfma_f32_16x16x32_bf16 v[96:99], v[168:171], v[192:195], v[96:99]
	v_mfma_f32_16x16x32_bf16 v[88:91], v[176:179], v[192:195], v[88:91]
	v_mfma_f32_16x16x32_bf16 v[80:83], v[168:171], v[210:213], v[80:83]
	v_mfma_f32_16x16x32_bf16 v[72:75], v[176:179], v[210:213], v[72:75]
	v_mfma_f32_16x16x32_bf16 v[68:71], v[168:171], v[218:221], v[68:71]
	v_mfma_f32_16x16x32_bf16 v[64:67], v[176:179], v[218:221], v[64:67]
	s_setprio 0
	s_barrier
; #define PG8_STAGE(bufoff, gbase, voff) do { _Pragma("unroll") for (int _i = 0; _i < 2; ++_i) \
;         __builtin_amdgcn_global_load_lds((const unsigned*)((const char*)(gbase) + (voff)[_i]), (LAS unsigned*)(lds + (bufoff) + ldsw + _i * 8192), 16, 0, 0); } while (0)
; #define PG8_LDA(dst, b, h) do { _Pragma("unroll") for (int m = 0; m < 4; ++m) _Pragma("unroll") for (int k = 0; k < 2; ++k) dst[m][k] = *(const LAS bf16x8*)(lds + PG8_SA(b, h) + aoff + m * 2048 + k * 1024); } while (0)
; #define PG8_MMA(ai, bj, At, Bt) do { __builtin_amdgcn_s_setprio(1); _Pragma("unroll") for (int m = 0; m < 4; ++m) _Pragma("unroll") for (int n = 0; n < 2; ++n) _Pragma("unroll") for (int k = 0; k < 2; ++k) \
;         acc[ai][bj][m][n] = __builtin_amdgcn_mfma_f32_16x16x32_bf16(Bt[n][k], At[m][k], acc[ai][bj][m][n], 0, 0, 0); __builtin_amdgcn_s_setprio(0); } while (0)
; #define PG8_WAIT_V(n) asm volatile("s_waitcnt vmcnt(" #n ")" ::: "memory")
; #define PG8_WAIT_L(n) asm volatile("s_waitcnt lgkmcnt(" #n ")" ::: "memory")
; #define PG8_BAR __builtin_amdgcn_s_barrier()
; #define PG8_SCHED __builtin_amdgcn_sched_barrier(0)
; template <class Epi, class Sched>
; DI void gemm_phase(const int wv, LAS unsigned char* lds, const int lda, const int ldb, const int K, const Sched& S, const Epi& E) {
;     ...
;             PG8_LDA(At, 1, 1); PG8_STAGE(PG8_SB(1, 0), b3, voffB); PG8_STAGE(PG8_SB(1, 1), b3 + hstepB, voffB); PG8_STAGE(PG8_SA(1, 0), a3, voffA);
;             PG8_WAIT_V(8); PG8_WAIT_L(0); PG8_BAR; PG8_MMA(1, 0, At, B0); PG8_MMA(1, 1, At, B1); PG8_BAR; PG8_SCHED;
;         }
;         if (wr == 0) PG8_BAR;
	s_add_i32 s20, s42, s26
	v_lshl_add_u64 v[154:155], v[154:155], 0, s[78:79]
	s_mov_b32 m0, s20
	ds_read_b128 v[180:183], v159 offset:49152
	ds_read_b128 v[184:187], v159 offset:50176
	ds_read_b128 v[188:191], v159 offset:51200
	ds_read_b128 v[192:195], v159 offset:52224
	ds_read_b128 v[196:199], v159 offset:53248
	ds_read_b128 v[210:213], v159 offset:54272
	ds_read_b128 v[214:217], v159 offset:55296
	ds_read_b128 v[218:221], v159 offset:56320
	global_load_lds_dwordx4 v[154:155], off
	s_add_i32 m0, s20, 0x2000
	s_add_u32 s18, s18, 0x80080
	v_lshl_add_u64 v[154:155], v[222:223], 0, s[78:79]
	s_addc_u32 s19, s19, 0
	s_add_i32 s20, s43, s26
	global_load_lds_dwordx4 v[154:155], off
	v_lshl_add_u64 v[154:155], s[18:19], 0, v[160:161]
	s_mov_b32 m0, s20
	s_nop 0
	global_load_lds_dwordx4 v[154:155], off
	v_lshl_add_u64 v[154:155], s[18:19], 0, v[144:145]
	s_add_i32 m0, s20, 0x2000
	s_nop 0
	global_load_lds_dwordx4 v[154:155], off
	v_lshl_add_u64 v[154:155], v[224:225], 0, s[78:79]
	s_mov_b32 m0, s35
	s_nop 0
	global_load_lds_dwordx4 v[154:155], off
	v_lshl_add_u64 v[154:155], v[226:227], 0, s[78:79]
	s_mov_b32 m0, s36
	s_nop 0
	global_load_lds_dwordx4 v[154:155], off
	s_waitcnt vmcnt(8)
	s_waitcnt lgkmcnt(0)
	s_barrier
	s_setprio 1
	s_waitcnt lgkmcnt(0)
	v_mfma_f32_16x16x32_bf16 v[60:63], v[128:131], v[180:183], v[60:63]
	v_mfma_f32_16x16x32_bf16 v[56:59], v[136:139], v[180:183], v[56:59]
	v_mfma_f32_16x16x32_bf16 v[52:55], v[128:131], v[188:191], v[52:55]
	v_mfma_f32_16x16x32_bf16 v[44:47], v[136:139], v[188:191], v[44:47]
	v_mfma_f32_16x16x32_bf16 v[36:39], v[128:131], v[196:199], v[36:39]
	v_mfma_f32_16x16x32_bf16 v[28:31], v[136:139], v[196:199], v[28:31]
	v_mfma_f32_16x16x32_bf16 v[20:23], v[128:131], v[214:217], v[20:23]
	v_mfma_f32_16x16x32_bf16 v[12:15], v[136:139], v[214:217], v[12:15]
	v_mfma_f32_16x16x32_bf16 v[60:63], v[132:135], v[184:187], v[60:63]
	v_mfma_f32_16x16x32_bf16 v[56:59], v[140:143], v[184:187], v[56:59]
	v_mfma_f32_16x16x32_bf16 v[52:55], v[132:135], v[192:195], v[52:55]
	v_mfma_f32_16x16x32_bf16 v[44:47], v[140:143], v[192:195], v[44:47]
	v_mfma_f32_16x16x32_bf16 v[36:39], v[132:135], v[210:213], v[36:39]
	v_mfma_f32_16x16x32_bf16 v[28:31], v[140:143], v[210:213], v[28:31]
	v_mfma_f32_16x16x32_bf16 v[20:23], v[132:135], v[218:221], v[20:23]
	v_mfma_f32_16x16x32_bf16 v[12:15], v[140:143], v[218:221], v[12:15]
	v_mfma_f32_16x16x32_bf16 v[48:51], v[162:165], v[180:183], v[48:51]
	v_mfma_f32_16x16x32_bf16 v[40:43], v[172:175], v[180:183], v[40:43]
	v_mfma_f32_16x16x32_bf16 v[32:35], v[162:165], v[188:191], v[32:35]
	v_mfma_f32_16x16x32_bf16 v[24:27], v[172:175], v[188:191], v[24:27]
	v_mfma_f32_16x16x32_bf16 v[16:19], v[162:165], v[196:199], v[16:19]
	v_mfma_f32_16x16x32_bf16 v[8:11], v[172:175], v[196:199], v[8:11]
	v_mfma_f32_16x16x32_bf16 v[4:7], v[162:165], v[214:217], v[4:7]
	v_mfma_f32_16x16x32_bf16 v[0:3], v[172:175], v[214:217], v[0:3]
	v_mfma_f32_16x16x32_bf16 v[48:51], v[168:171], v[184:187], v[48:51]
	v_mfma_f32_16x16x32_bf16 v[40:43], v[176:179], v[184:187], v[40:43]
	v_mfma_f32_16x16x32_bf16 v[32:35], v[168:171], v[192:195], v[32:35]
	v_mfma_f32_16x16x32_bf16 v[24:27], v[176:179], v[192:195], v[24:27]
	v_mfma_f32_16x16x32_bf16 v[16:19], v[168:171], v[210:213], v[16:19]
	v_mfma_f32_16x16x32_bf16 v[8:11], v[176:179], v[210:213], v[8:11]
	v_mfma_f32_16x16x32_bf16 v[4:7], v[168:171], v[218:221], v[4:7]
	v_mfma_f32_16x16x32_bf16 v[0:3], v[176:179], v[218:221], v[0:3]
	s_setprio 0
	s_barrier
	s_add_i32 s41, s41, 2
	s_add_u32 s11, s11, 0x100
	s_addc_u32 s40, s40, 0
	s_add_u32 s16, s16, 0x100
	s_addc_u32 s17, s17, 0
	s_cmp_gt_u32 s41, 29
	s_cbranch_scc0 .LBB0_686
	s_and_b64 vcc, exec, s[8:9]
	s_cbranch_vccz .LBB0_689
	s_barrier

; #define PG8_STAGE(bufoff, gbase, voff) do { _Pragma("unroll") for (int _i = 0; _i < 2; ++_i) \
;         __builtin_amdgcn_global_load_lds((const unsigned*)((const char*)(gbase) + (voff)[_i]), (LAS unsigned*)(lds + (bufoff) + ldsw + _i * 8192), 16, 0, 0); } while (0)
; #define PG8_LDA(dst, b, h) do { _Pragma("unroll") for (int m = 0; m < 4; ++m) _Pragma("unroll") for (int k = 0; k < 2; ++k) dst[m][k] = *(const LAS bf16x8*)(lds + PG8_SA(b, h) + aoff + m * 2048 + k * 1024); } while (0)
; #define PG8_LDB(dst, b, h) do { _Pragma("unroll") for (int n = 0; n < 2; ++n) _Pragma("unroll") for (int k = 0; k < 2; ++k) dst[n][k] = *(const LAS bf16x8*)(lds + PG8_SB(b, h) + boff + n * 2048 + k * 1024); } while (0)
; #define PG8_MMA(ai, bj, At, Bt) do { __builtin_amdgcn_s_setprio(1); _Pragma("unroll") for (int m = 0; m < 4; ++m) _Pragma("unroll") for (int n = 0; n < 2; ++n) _Pragma("unroll") for (int k = 0; k < 2; ++k) \
;         acc[ai][bj][m][n] = __builtin_amdgcn_mfma_f32_16x16x32_bf16(Bt[n][k], At[m][k], acc[ai][bj][m][n], 0, 0, 0); __builtin_amdgcn_s_setprio(0); } while (0)
; #define PG8_WAIT_V(n) asm volatile("s_waitcnt vmcnt(" #n ")" ::: "memory")
; #define PG8_WAIT_L(n) asm volatile("s_waitcnt lgkmcnt(" #n ")" ::: "memory")
; #define PG8_BAR __builtin_amdgcn_s_barrier()
; #define PG8_SCHED __builtin_amdgcn_sched_barrier(0)
; template <class Epi, class Sched>
; DI void gemm_phase(const int wv, LAS unsigned char* lds, const int lda, const int ldb, const int K, const Sched& S, const Epi& E) {
;     ...
;             const char* a1 = cA + (size_t)(t + 1) * kstep;
;             const char* a2 = last ? nA : cA + (size_t)(t + 2) * kstep; const char* b2 = last ? nB : cB + (size_t)(t + 2) * kstep;
;             const char* a3 = a2 + kstep; const char* b3 = b2 + kstep;
;             PG8_LDB(B0, 0, 0); PG8_LDB(B1, 0, 1); PG8_SCHED; PG8_LDA(At, 0, 0); PG8_STAGE(PG8_SA(1, 1), a1 + hstepA, voffA);
;             PG8_WAIT_V(8); PG8_WAIT_L(0); PG8_BAR; PG8_MMA(0, 0, At, B0); PG8_MMA(0, 1, At, B1); PG8_BAR; PG8_SCHED;
;             PG8_LDA(At, 0, 1); PG8_STAGE(PG8_SB(0, 0), b2, voffB); PG8_STAGE(PG8_SB(0, 1), b2 + hstepB, voffB); PG8_STAGE(PG8_SA(0, 0), a2, voffA);
;             PG8_WAIT_V(8); PG8_WAIT_L(0); PG8_BAR; PG8_MMA(1, 0, At, B0); PG8_MMA(1, 1, At, B1); PG8_BAR; PG8_SCHED;
.LBB0_825:
	s_add_u32 s20, s18, 0xfff80080
	s_addc_u32 s21, s19, -1
	s_add_i32 s42, 0, 0x10000
	s_cmp_eq_u32 s41, 28
	s_cselect_b32 s23, s15, s21
	s_cselect_b32 s22, s14, s20
	s_cselect_b32 s21, s17, s40
	s_cselect_b32 s20, s16, s13
	s_add_i32 s44, 0, 0x14000
	v_add_u32_e32 v154, s42, v139
	v_add_u32_e32 v158, s44, v139
	ds_read_b128 v[142:145], v154
	ds_read_b128 v[146:149], v154 offset:1024
	ds_read_b128 v[150:153], v154 offset:2048
	ds_read_b128 v[154:157], v154 offset:3072
	ds_read_b128 v[162:165], v158
	ds_read_b128 v[168:171], v158 offset:1024
	ds_read_b128 v[172:175], v158 offset:2048
	ds_read_b128 v[176:179], v158 offset:3072
	v_lshl_add_u64 v[158:159], s[18:19], 0, v[136:137]
	s_add_i32 m0, s29, 0xc000
	ds_read_b128 v[180:183], v141
	ds_read_b128 v[184:187], v141 offset:1024
	ds_read_b128 v[188:191], v141 offset:2048
	ds_read_b128 v[192:195], v141 offset:3072
	ds_read_b128 v[196:199], v141 offset:4096
	ds_read_b128 v[210:213], v141 offset:5120
	ds_read_b128 v[214:217], v141 offset:6144
	ds_read_b128 v[218:221], v141 offset:7168
	global_load_lds_dwordx4 v[158:159], off
	v_lshl_add_u64 v[158:159], s[18:19], 0, v[134:135]
	s_add_i32 m0, s29, 0xe000
	s_nop 0
	global_load_lds_dwordx4 v[158:159], off
	s_waitcnt vmcnt(8)
	s_waitcnt lgkmcnt(0)
	s_barrier
	s_setprio 1
	s_waitcnt lgkmcnt(0)
	v_mfma_f32_16x16x32_bf16 v[124:127], v[142:145], v[180:183], v[124:127]
	v_mfma_f32_16x16x32_bf16 v[120:123], v[150:153], v[180:183], v[120:123]
	v_mfma_f32_16x16x32_bf16 v[108:111], v[142:145], v[188:191], v[108:111]
	v_mfma_f32_16x16x32_bf16 v[104:107], v[150:153], v[188:191], v[104:107]
	v_mfma_f32_16x16x32_bf16 v[92:95], v[142:145], v[196:199], v[92:95]
	v_mfma_f32_16x16x32_bf16 v[88:91], v[150:153], v[196:199], v[88:91]
	v_mfma_f32_16x16x32_bf16 v[76:79], v[142:145], v[214:217], v[76:79]
	v_mfma_f32_16x16x32_bf16 v[72:75], v[150:153], v[214:217], v[72:75]
	v_mfma_f32_16x16x32_bf16 v[124:127], v[146:149], v[184:187], v[124:127]
	v_mfma_f32_16x16x32_bf16 v[120:123], v[154:157], v[184:187], v[120:123]
	v_mfma_f32_16x16x32_bf16 v[108:111], v[146:149], v[192:195], v[108:111]
	v_mfma_f32_16x16x32_bf16 v[104:107], v[154:157], v[192:195], v[104:107]
	v_mfma_f32_16x16x32_bf16 v[92:95], v[146:149], v[210:213], v[92:95]
	v_mfma_f32_16x16x32_bf16 v[88:91], v[154:157], v[210:213], v[88:91]
	v_mfma_f32_16x16x32_bf16 v[76:79], v[146:149], v[218:221], v[76:79]
	v_mfma_f32_16x16x32_bf16 v[72:75], v[154:157], v[218:221], v[72:75]
	v_mfma_f32_16x16x32_bf16 v[116:119], v[162:165], v[180:183], v[116:119]
	v_mfma_f32_16x16x32_bf16 v[112:115], v[172:175], v[180:183], v[112:115]
	v_mfma_f32_16x16x32_bf16 v[100:103], v[162:165], v[188:191], v[100:103]
	v_mfma_f32_16x16x32_bf16 v[96:99], v[172:175], v[188:191], v[96:99]
	v_mfma_f32_16x16x32_bf16 v[84:87], v[162:165], v[196:199], v[84:87]
	v_mfma_f32_16x16x32_bf16 v[80:83], v[172:175], v[196:199], v[80:83]
	v_mfma_f32_16x16x32_bf16 v[68:71], v[162:165], v[214:217], v[68:71]
	v_mfma_f32_16x16x32_bf16 v[64:67], v[172:175], v[214:217], v[64:67]
	v_mfma_f32_16x16x32_bf16 v[116:119], v[168:171], v[184:187], v[116:119]
	v_mfma_f32_16x16x32_bf16 v[112:115], v[176:179], v[184:187], v[112:115]
	v_mfma_f32_16x16x32_bf16 v[100:103], v[168:171], v[192:195], v[100:103]
	v_mfma_f32_16x16x32_bf16 v[96:99], v[176:179], v[192:195], v[96:99]
	v_mfma_f32_16x16x32_bf16 v[84:87], v[168:171], v[210:213], v[84:87]
	v_mfma_f32_16x16x32_bf16 v[80:83], v[176:179], v[210:213], v[80:83]
	v_mfma_f32_16x16x32_bf16 v[68:71], v[168:171], v[218:221], v[68:71]
	v_mfma_f32_16x16x32_bf16 v[64:67], v[176:179], v[218:221], v[64:67]
	s_setprio 0
	s_barrier
	s_add_i32 s42, s42, s28
	v_lshl_add_u64 v[158:159], s[20:21], 0, v[160:161]
	s_mov_b32 m0, s42
	ds_read_b128 v[180:183], v141 offset:16384
	ds_read_b128 v[184:187], v141 offset:17408
	ds_read_b128 v[188:191], v141 offset:18432
	ds_read_b128 v[192:195], v141 offset:19456
	ds_read_b128 v[196:199], v141 offset:20480
	ds_read_b128 v[210:213], v141 offset:21504
	ds_read_b128 v[214:217], v141 offset:22528
	ds_read_b128 v[218:221], v141 offset:23552
	global_load_lds_dwordx4 v[158:159], off
	s_add_i32 m0, s42, 0x2000
	s_add_u32 s42, s20, 0x80000
	v_lshl_add_u64 v[222:223], s[20:21], 0, v[128:129]
	s_addc_u32 s43, s21, 0
	s_add_i32 s44, s44, s28
	global_load_lds_dwordx4 v[222:223], off
	v_lshl_add_u64 v[224:225], s[42:43], 0, v[160:161]
	s_mov_b32 m0, s44
	v_lshl_add_u64 v[226:227], s[22:23], 0, v[130:131]
	global_load_lds_dwordx4 v[224:225], off
	v_lshl_add_u64 v[224:225], s[42:43], 0, v[128:129]
	s_add_i32 m0, s44, 0x2000
	s_nop 0
	global_load_lds_dwordx4 v[224:225], off
	v_lshl_add_u64 v[224:225], s[22:23], 0, v[132:133]
	s_mov_b32 m0, s29
	s_nop 0
	global_load_lds_dwordx4 v[224:225], off
	s_mov_b32 m0, s30
	s_nop 0
	global_load_lds_dwordx4 v[226:227], off
	s_waitcnt vmcnt(8)
	s_waitcnt lgkmcnt(0)
	s_barrier
; #define PG8_STAGE(bufoff, gbase, voff) do { _Pragma("unroll") for (int _i = 0; _i < 2; ++_i) \
;         __builtin_amdgcn_global_load_lds((const unsigned*)((const char*)(gbase) + (voff)[_i]), (LAS unsigned*)(lds + (bufoff) + ldsw + _i * 8192), 16, 0, 0); } while (0)
; #define PG8_LDA(dst, b, h) do { _Pragma("unroll") for (int m = 0; m < 4; ++m) _Pragma("unroll") for (int k = 0; k < 2; ++k) dst[m][k] = *(const LAS bf16x8*)(lds + PG8_SA(b, h) + aoff + m * 2048 + k * 1024); } while (0)
; #define PG8_LDB(dst, b, h) do { _Pragma("unroll") for (int n = 0; n < 2; ++n) _Pragma("unroll") for (int k = 0; k < 2; ++k) dst[n][k] = *(const LAS bf16x8*)(lds + PG8_SB(b, h) + boff + n * 2048 + k * 1024); } while (0)
; #define PG8_MMA(ai, bj, At, Bt) do { __builtin_amdgcn_s_setprio(1); _Pragma("unroll") for (int m = 0; m < 4; ++m) _Pragma("unroll") for (int n = 0; n < 2; ++n) _Pragma("unroll") for (int k = 0; k < 2; ++k) \
;         acc[ai][bj][m][n] = __builtin_amdgcn_mfma_f32_16x16x32_bf16(Bt[n][k], At[m][k], acc[ai][bj][m][n], 0, 0, 0); __builtin_amdgcn_s_setprio(0); } while (0)
; #define PG8_WAIT_V(n) asm volatile("s_waitcnt vmcnt(" #n ")" ::: "memory")
; #define PG8_WAIT_L(n) asm volatile("s_waitcnt lgkmcnt(" #n ")" ::: "memory")
; #define PG8_BAR __builtin_amdgcn_s_barrier()
; #define PG8_SCHED __builtin_amdgcn_sched_barrier(0)
; template <class Epi, class Sched>
; DI void gemm_phase(const int wv, LAS unsigned char* lds, const int lda, const int ldb, const int K, const Sched& S, const Epi& E) {
;     ...
;             PG8_WAIT_V(8); PG8_WAIT_L(0); PG8_BAR; PG8_MMA(1, 0, At, B0); PG8_MMA(1, 1, At, B1); PG8_BAR; PG8_SCHED;
;             PG8_LDB(B0, 1, 0); PG8_LDB(B1, 1, 1); PG8_SCHED; PG8_LDA(At, 1, 0); PG8_STAGE(PG8_SA(0, 1), a2 + hstepA, voffA);
;             PG8_WAIT_V(8); PG8_WAIT_L(0); PG8_BAR; PG8_MMA(0, 0, At, B0); PG8_MMA(0, 1, At, B1); PG8_BAR; PG8_SCHED;
	s_setprio 1
	s_waitcnt lgkmcnt(0)
	v_mfma_f32_16x16x32_bf16 v[60:63], v[142:145], v[180:183], v[60:63]
	v_mfma_f32_16x16x32_bf16 v[56:59], v[150:153], v[180:183], v[56:59]
	v_mfma_f32_16x16x32_bf16 v[44:47], v[142:145], v[188:191], v[44:47]
	v_mfma_f32_16x16x32_bf16 v[40:43], v[150:153], v[188:191], v[40:43]
	v_mfma_f32_16x16x32_bf16 v[28:31], v[142:145], v[196:199], v[28:31]
	v_mfma_f32_16x16x32_bf16 v[24:27], v[150:153], v[196:199], v[24:27]
	v_mfma_f32_16x16x32_bf16 v[12:15], v[142:145], v[214:217], v[12:15]
	v_mfma_f32_16x16x32_bf16 v[8:11], v[150:153], v[214:217], v[8:11]
	v_mfma_f32_16x16x32_bf16 v[60:63], v[146:149], v[184:187], v[60:63]
	v_mfma_f32_16x16x32_bf16 v[56:59], v[154:157], v[184:187], v[56:59]
	v_mfma_f32_16x16x32_bf16 v[44:47], v[146:149], v[192:195], v[44:47]
	v_mfma_f32_16x16x32_bf16 v[40:43], v[154:157], v[192:195], v[40:43]
	v_mfma_f32_16x16x32_bf16 v[28:31], v[146:149], v[210:213], v[28:31]
	v_mfma_f32_16x16x32_bf16 v[24:27], v[154:157], v[210:213], v[24:27]
	v_mfma_f32_16x16x32_bf16 v[12:15], v[146:149], v[218:221], v[12:15]
	v_mfma_f32_16x16x32_bf16 v[8:11], v[154:157], v[218:221], v[8:11]
	v_mfma_f32_16x16x32_bf16 v[52:55], v[162:165], v[180:183], v[52:55]
	v_mfma_f32_16x16x32_bf16 v[48:51], v[172:175], v[180:183], v[48:51]
	v_mfma_f32_16x16x32_bf16 v[36:39], v[162:165], v[188:191], v[36:39]
	v_mfma_f32_16x16x32_bf16 v[32:35], v[172:175], v[188:191], v[32:35]
	v_mfma_f32_16x16x32_bf16 v[20:23], v[162:165], v[196:199], v[20:23]
	v_mfma_f32_16x16x32_bf16 v[16:19], v[172:175], v[196:199], v[16:19]
	v_mfma_f32_16x16x32_bf16 v[4:7], v[162:165], v[214:217], v[4:7]
	v_mfma_f32_16x16x32_bf16 v[0:3], v[172:175], v[214:217], v[0:3]
	v_mfma_f32_16x16x32_bf16 v[52:55], v[168:171], v[184:187], v[52:55]
	v_mfma_f32_16x16x32_bf16 v[48:51], v[176:179], v[184:187], v[48:51]
	v_mfma_f32_16x16x32_bf16 v[36:39], v[168:171], v[192:195], v[36:39]
	v_mfma_f32_16x16x32_bf16 v[32:35], v[176:179], v[192:195], v[32:35]
	v_mfma_f32_16x16x32_bf16 v[20:23], v[168:171], v[210:213], v[20:23]
	v_mfma_f32_16x16x32_bf16 v[16:19], v[176:179], v[210:213], v[16:19]
	v_mfma_f32_16x16x32_bf16 v[4:7], v[168:171], v[218:221], v[4:7]
	v_mfma_f32_16x16x32_bf16 v[0:3], v[176:179], v[218:221], v[0:3]
	s_setprio 0
	s_barrier
	s_add_i32 s42, 0, 0x18000
	s_add_i32 s43, 0, 0x1c000
	v_add_u32_e32 v154, s42, v139
	v_add_u32_e32 v176, s43, v139
	ds_read_b128 v[142:145], v154
	ds_read_b128 v[146:149], v154 offset:1024
	ds_read_b128 v[150:153], v154 offset:2048
	ds_read_b128 v[154:157], v154 offset:3072
	ds_read_b128 v[162:165], v176
	ds_read_b128 v[168:171], v176 offset:1024
	ds_read_b128 v[172:175], v176 offset:2048
	ds_read_b128 v[176:179], v176 offset:3072
	s_add_u32 s22, s22, 0x80000
	s_addc_u32 s23, s23, 0
	s_mov_b32 m0, s31
	v_lshl_add_u64 v[228:229], s[22:23], 0, v[132:133]
	ds_read_b128 v[180:183], v141 offset:32768
	ds_read_b128 v[184:187], v141 offset:33792
	ds_read_b128 v[188:191], v141 offset:34816
	ds_read_b128 v[192:195], v141 offset:35840
	ds_read_b128 v[196:199], v141 offset:36864
	ds_read_b128 v[210:213], v141 offset:37888
	ds_read_b128 v[214:217], v141 offset:38912
	ds_read_b128 v[218:221], v141 offset:39936
	global_load_lds_dwordx4 v[228:229], off
	v_lshl_add_u64 v[228:229], s[22:23], 0, v[130:131]
	s_mov_b32 m0, s34
	s_nop 0
	global_load_lds_dwordx4 v[228:229], off
	s_waitcnt vmcnt(8)
	s_waitcnt lgkmcnt(0)
	s_barrier
	s_setprio 1
	s_waitcnt lgkmcnt(0)
	v_mfma_f32_16x16x32_bf16 v[124:127], v[142:145], v[180:183], v[124:127]
	v_mfma_f32_16x16x32_bf16 v[120:123], v[150:153], v[180:183], v[120:123]
	v_mfma_f32_16x16x32_bf16 v[108:111], v[142:145], v[188:191], v[108:111]
	v_mfma_f32_16x16x32_bf16 v[104:107], v[150:153], v[188:191], v[104:107]
	v_mfma_f32_16x16x32_bf16 v[92:95], v[142:145], v[196:199], v[92:95]
	v_mfma_f32_16x16x32_bf16 v[88:91], v[150:153], v[196:199], v[88:91]
	v_mfma_f32_16x16x32_bf16 v[76:79], v[142:145], v[214:217], v[76:79]
	v_mfma_f32_16x16x32_bf16 v[72:75], v[150:153], v[214:217], v[72:75]
	v_mfma_f32_16x16x32_bf16 v[124:127], v[146:149], v[184:187], v[124:127]
	v_mfma_f32_16x16x32_bf16 v[120:123], v[154:157], v[184:187], v[120:123]
	v_mfma_f32_16x16x32_bf16 v[108:111], v[146:149], v[192:195], v[108:111]
	v_mfma_f32_16x16x32_bf16 v[104:107], v[154:157], v[192:195], v[104:107]
	v_mfma_f32_16x16x32_bf16 v[92:95], v[146:149], v[210:213], v[92:95]
	v_mfma_f32_16x16x32_bf16 v[88:91], v[154:157], v[210:213], v[88:91]
	v_mfma_f32_16x16x32_bf16 v[76:79], v[146:149], v[218:221], v[76:79]
	v_mfma_f32_16x16x32_bf16 v[72:75], v[154:157], v[218:221], v[72:75]
	v_mfma_f32_16x16x32_bf16 v[116:119], v[162:165], v[180:183], v[116:119]
	v_mfma_f32_16x16x32_bf16 v[112:115], v[172:175], v[180:183], v[112:115]
	v_mfma_f32_16x16x32_bf16 v[100:103], v[162:165], v[188:191], v[100:103]
	v_mfma_f32_16x16x32_bf16 v[96:99], v[172:175], v[188:191], v[96:99]
	v_mfma_f32_16x16x32_bf16 v[84:87], v[162:165], v[196:199], v[84:87]
	v_mfma_f32_16x16x32_bf16 v[80:83], v[172:175], v[196:199], v[80:83]
	v_mfma_f32_16x16x32_bf16 v[68:71], v[162:165], v[214:217], v[68:71]
	v_mfma_f32_16x16x32_bf16 v[64:67], v[172:175], v[214:217], v[64:67]
	v_mfma_f32_16x16x32_bf16 v[116:119], v[168:171], v[184:187], v[116:119]
	v_mfma_f32_16x16x32_bf16 v[112:115], v[176:179], v[184:187], v[112:115]
	v_mfma_f32_16x16x32_bf16 v[100:103], v[168:171], v[192:195], v[100:103]
	v_mfma_f32_16x16x32_bf16 v[96:99], v[176:179], v[192:195], v[96:99]
	v_mfma_f32_16x16x32_bf16 v[84:87], v[168:171], v[210:213], v[84:87]
	v_mfma_f32_16x16x32_bf16 v[80:83], v[176:179], v[210:213], v[80:83]
	v_mfma_f32_16x16x32_bf16 v[68:71], v[168:171], v[218:221], v[68:71]
	v_mfma_f32_16x16x32_bf16 v[64:67], v[176:179], v[218:221], v[64:67]
	s_setprio 0
	s_barrier
; #define PG8_STAGE(bufoff, gbase, voff) do { _Pragma("unroll") for (int _i = 0; _i < 2; ++_i) \
;         __builtin_amdgcn_global_load_lds((const unsigned*)((const char*)(gbase) + (voff)[_i]), (LAS unsigned*)(lds + (bufoff) + ldsw + _i * 8192), 16, 0, 0); } while (0)
; #define PG8_LDA(dst, b, h) do { _Pragma("unroll") for (int m = 0; m < 4; ++m) _Pragma("unroll") for (int k = 0; k < 2; ++k) dst[m][k] = *(const LAS bf16x8*)(lds + PG8_SA(b, h) + aoff + m * 2048 + k * 1024); } while (0)
; #define PG8_MMA(ai, bj, At, Bt) do { __builtin_amdgcn_s_setprio(1); _Pragma("unroll") for (int m = 0; m < 4; ++m) _Pragma("unroll") for (int n = 0; n < 2; ++n) _Pragma("unroll") for (int k = 0; k < 2; ++k) \
;         acc[ai][bj][m][n] = __builtin_amdgcn_mfma_f32_16x16x32_bf16(Bt[n][k], At[m][k], acc[ai][bj][m][n], 0, 0, 0); __builtin_amdgcn_s_setprio(0); } while (0)
; #define PG8_WAIT_V(n) asm volatile("s_waitcnt vmcnt(" #n ")" ::: "memory")
; #define PG8_WAIT_L(n) asm volatile("s_waitcnt lgkmcnt(" #n ")" ::: "memory")
; #define PG8_BAR __builtin_amdgcn_s_barrier()
; #define PG8_SCHED __builtin_amdgcn_sched_barrier(0)
; template <class Epi, class Sched>
; DI void gemm_phase(const int wv, LAS unsigned char* lds, const int lda, const int ldb, const int K, const Sched& S, const Epi& E) {
;     ...
;             PG8_LDA(At, 1, 1); PG8_STAGE(PG8_SB(1, 0), b3, voffB); PG8_STAGE(PG8_SB(1, 1), b3 + hstepB, voffB); PG8_STAGE(PG8_SA(1, 0), a3, voffA);
;             PG8_WAIT_V(8); PG8_WAIT_L(0); PG8_BAR; PG8_MMA(1, 0, At, B0); PG8_MMA(1, 1, At, B1); PG8_BAR; PG8_SCHED;
;         }
;         if (wr == 0) PG8_BAR;
	s_add_i32 s22, s42, s28
	v_lshl_add_u64 v[158:159], v[158:159], 0, s[78:79]
	s_mov_b32 m0, s22
	ds_read_b128 v[180:183], v141 offset:49152
	ds_read_b128 v[184:187], v141 offset:50176
	ds_read_b128 v[188:191], v141 offset:51200
	ds_read_b128 v[192:195], v141 offset:52224
	ds_read_b128 v[196:199], v141 offset:53248
	ds_read_b128 v[210:213], v141 offset:54272
	ds_read_b128 v[214:217], v141 offset:55296
	ds_read_b128 v[218:221], v141 offset:56320
	global_load_lds_dwordx4 v[158:159], off
	s_add_i32 m0, s22, 0x2000
	s_add_u32 s20, s20, 0x80080
	v_lshl_add_u64 v[158:159], v[222:223], 0, s[78:79]
	s_addc_u32 s21, s21, 0
	s_add_i32 s22, s43, s28
	global_load_lds_dwordx4 v[158:159], off
	v_lshl_add_u64 v[158:159], s[20:21], 0, v[160:161]
	s_mov_b32 m0, s22
	s_nop 0
	global_load_lds_dwordx4 v[158:159], off
	v_lshl_add_u64 v[158:159], s[20:21], 0, v[128:129]
	s_add_i32 m0, s22, 0x2000
	s_nop 0
	global_load_lds_dwordx4 v[158:159], off
	v_lshl_add_u64 v[158:159], v[224:225], 0, s[78:79]
	s_mov_b32 m0, s35
	s_nop 0
	global_load_lds_dwordx4 v[158:159], off
	v_lshl_add_u64 v[158:159], v[226:227], 0, s[78:79]
	s_mov_b32 m0, s36
	s_nop 0
	global_load_lds_dwordx4 v[158:159], off
	s_waitcnt vmcnt(8)
	s_waitcnt lgkmcnt(0)
	s_barrier
	s_setprio 1
	s_waitcnt lgkmcnt(0)
	v_mfma_f32_16x16x32_bf16 v[60:63], v[142:145], v[180:183], v[60:63]
	v_mfma_f32_16x16x32_bf16 v[56:59], v[150:153], v[180:183], v[56:59]
	v_mfma_f32_16x16x32_bf16 v[44:47], v[142:145], v[188:191], v[44:47]
	v_mfma_f32_16x16x32_bf16 v[40:43], v[150:153], v[188:191], v[40:43]
	v_mfma_f32_16x16x32_bf16 v[28:31], v[142:145], v[196:199], v[28:31]
	v_mfma_f32_16x16x32_bf16 v[24:27], v[150:153], v[196:199], v[24:27]
	v_mfma_f32_16x16x32_bf16 v[12:15], v[142:145], v[214:217], v[12:15]
	v_mfma_f32_16x16x32_bf16 v[8:11], v[150:153], v[214:217], v[8:11]
	v_mfma_f32_16x16x32_bf16 v[60:63], v[146:149], v[184:187], v[60:63]
	v_mfma_f32_16x16x32_bf16 v[56:59], v[154:157], v[184:187], v[56:59]
	v_mfma_f32_16x16x32_bf16 v[44:47], v[146:149], v[192:195], v[44:47]
	v_mfma_f32_16x16x32_bf16 v[40:43], v[154:157], v[192:195], v[40:43]
	v_mfma_f32_16x16x32_bf16 v[28:31], v[146:149], v[210:213], v[28:31]
	v_mfma_f32_16x16x32_bf16 v[24:27], v[154:157], v[210:213], v[24:27]
	v_mfma_f32_16x16x32_bf16 v[12:15], v[146:149], v[218:221], v[12:15]
	v_mfma_f32_16x16x32_bf16 v[8:11], v[154:157], v[218:221], v[8:11]
	v_mfma_f32_16x16x32_bf16 v[52:55], v[162:165], v[180:183], v[52:55]
	v_mfma_f32_16x16x32_bf16 v[48:51], v[172:175], v[180:183], v[48:51]
	v_mfma_f32_16x16x32_bf16 v[36:39], v[162:165], v[188:191], v[36:39]
	v_mfma_f32_16x16x32_bf16 v[32:35], v[172:175], v[188:191], v[32:35]
	v_mfma_f32_16x16x32_bf16 v[20:23], v[162:165], v[196:199], v[20:23]
	v_mfma_f32_16x16x32_bf16 v[16:19], v[172:175], v[196:199], v[16:19]
	v_mfma_f32_16x16x32_bf16 v[4:7], v[162:165], v[214:217], v[4:7]
	v_mfma_f32_16x16x32_bf16 v[0:3], v[172:175], v[214:217], v[0:3]
	v_mfma_f32_16x16x32_bf16 v[52:55], v[168:171], v[184:187], v[52:55]
	v_mfma_f32_16x16x32_bf16 v[48:51], v[176:179], v[184:187], v[48:51]
	v_mfma_f32_16x16x32_bf16 v[36:39], v[168:171], v[192:195], v[36:39]
	v_mfma_f32_16x16x32_bf16 v[32:35], v[176:179], v[192:195], v[32:35]
	v_mfma_f32_16x16x32_bf16 v[20:23], v[168:171], v[210:213], v[20:23]
	v_mfma_f32_16x16x32_bf16 v[16:19], v[176:179], v[210:213], v[16:19]
	v_mfma_f32_16x16x32_bf16 v[4:7], v[168:171], v[218:221], v[4:7]
	v_mfma_f32_16x16x32_bf16 v[0:3], v[176:179], v[218:221], v[0:3]
	s_setprio 0
	s_barrier
	s_add_i32 s41, s41, 2
	s_add_u32 s13, s13, 0x100
	s_addc_u32 s40, s40, 0
	s_add_u32 s18, s18, 0x100
	s_addc_u32 s19, s19, 0
	s_cmp_gt_u32 s41, 29
	s_cbranch_scc0 .LBB0_825
	s_and_b64 vcc, exec, s[10:11]
	s_cbranch_vccz .LBB0_828
	s_barrier

; #define PG8_STAGE(bufoff, gbase, voff) do { _Pragma("unroll") for (int _i = 0; _i < 2; ++_i) \
;         __builtin_amdgcn_global_load_lds((const unsigned*)((const char*)(gbase) + (voff)[_i]), (LAS unsigned*)(lds + (bufoff) + ldsw + _i * 8192), 16, 0, 0); } while (0)
; #define PG8_LDA(dst, b, h) do { _Pragma("unroll") for (int m = 0; m < 4; ++m) _Pragma("unroll") for (int k = 0; k < 2; ++k) dst[m][k] = *(const LAS bf16x8*)(lds + PG8_SA(b, h) + aoff + m * 2048 + k * 1024); } while (0)
; #define PG8_LDB(dst, b, h) do { _Pragma("unroll") for (int n = 0; n < 2; ++n) _Pragma("unroll") for (int k = 0; k < 2; ++k) dst[n][k] = *(const LAS bf16x8*)(lds + PG8_SB(b, h) + boff + n * 2048 + k * 1024); } while (0)
; #define PG8_MMA(ai, bj, At, Bt) do { __builtin_amdgcn_s_setprio(1); _Pragma("unroll") for (int m = 0; m < 4; ++m) _Pragma("unroll") for (int n = 0; n < 2; ++n) _Pragma("unroll") for (int k = 0; k < 2; ++k) \
;         acc[ai][bj][m][n] = __builtin_amdgcn_mfma_f32_16x16x32_bf16(Bt[n][k], At[m][k], acc[ai][bj][m][n], 0, 0, 0); __builtin_amdgcn_s_setprio(0); } while (0)
; #define PG8_WAIT_V(n) asm volatile("s_waitcnt vmcnt(" #n ")" ::: "memory")
; #define PG8_WAIT_L(n) asm volatile("s_waitcnt lgkmcnt(" #n ")" ::: "memory")
; #define PG8_BAR __builtin_amdgcn_s_barrier()
; #define PG8_SCHED __builtin_amdgcn_sched_barrier(0)
; template <class Epi, class Sched>
; DI void gemm_phase(const int wv, LAS unsigned char* lds, const int lda, const int ldb, const int K, const Sched& S, const Epi& E) {
;     ...
;             const char* a1 = cA + (size_t)(t + 1) * kstep;
;             const char* a2 = last ? nA : cA + (size_t)(t + 2) * kstep; const char* b2 = last ? nB : cB + (size_t)(t + 2) * kstep;
;             const char* a3 = a2 + kstep; const char* b3 = b2 + kstep;
;             PG8_LDB(B0, 0, 0); PG8_LDB(B1, 0, 1); PG8_SCHED; PG8_LDA(At, 0, 0); PG8_STAGE(PG8_SA(1, 1), a1 + hstepA, voffA);
;             PG8_WAIT_V(8); PG8_WAIT_L(0); PG8_BAR; PG8_MMA(0, 0, At, B0); PG8_MMA(0, 1, At, B1); PG8_BAR; PG8_SCHED;
;             PG8_LDA(At, 0, 1); PG8_STAGE(PG8_SB(0, 0), b2, voffB); PG8_STAGE(PG8_SB(0, 1), b2 + hstepB, voffB); PG8_STAGE(PG8_SA(0, 0), a2, voffA);
;             PG8_WAIT_V(8); PG8_WAIT_L(0); PG8_BAR; PG8_MMA(1, 0, At, B0); PG8_MMA(1, 1, At, B1); PG8_BAR; PG8_SCHED;
.LBB0_906:
	s_add_u32 s14, s12, 0xffea0080
	s_addc_u32 s15, s13, -1
	s_add_i32 s40, 0, 0x10000
	s_cmpk_eq_i32 s39, 0x54
	s_cselect_b32 s17, s9, s15
	s_cselect_b32 s16, s8, s14
	s_cselect_b32 s15, s11, s38
	s_cselect_b32 s14, s10, s37
	s_add_i32 s42, 0, 0x14000
	v_add_u32_e32 v76, s40, v157
	v_add_u32_e32 v154, s42, v157
	ds_read_b128 v[48:51], v76
	ds_read_b128 v[52:55], v76 offset:1024
	ds_read_b128 v[72:75], v76 offset:2048
	ds_read_b128 v[76:79], v76 offset:3072
	ds_read_b128 v[162:165], v154
	ds_read_b128 v[168:171], v154 offset:1024
	ds_read_b128 v[172:175], v154 offset:2048
	ds_read_b128 v[176:179], v154 offset:3072
	v_lshl_add_u64 v[154:155], s[12:13], 0, v[152:153]
	s_add_i32 m0, s23, 0xc000
	ds_read_b128 v[180:183], v159
	ds_read_b128 v[184:187], v159 offset:1024
	ds_read_b128 v[188:191], v159 offset:2048
	ds_read_b128 v[192:195], v159 offset:3072
	ds_read_b128 v[196:199], v159 offset:4096
	ds_read_b128 v[210:213], v159 offset:5120
	ds_read_b128 v[214:217], v159 offset:6144
	ds_read_b128 v[218:221], v159 offset:7168
	global_load_lds_dwordx4 v[154:155], off
	v_lshl_add_u64 v[154:155], s[12:13], 0, v[150:151]
	s_add_i32 m0, s23, 0xe000
	s_nop 0
	global_load_lds_dwordx4 v[154:155], off
	s_waitcnt vmcnt(8)
	s_waitcnt lgkmcnt(0)
	s_barrier
	s_setprio 1
	s_waitcnt lgkmcnt(0)
	v_mfma_f32_16x16x32_bf16 v[140:143], v[48:51], v[180:183], v[140:143]
	v_mfma_f32_16x16x32_bf16 v[136:139], v[72:75], v[180:183], v[136:139]
	v_mfma_f32_16x16x32_bf16 v[124:127], v[48:51], v[188:191], v[124:127]
	v_mfma_f32_16x16x32_bf16 v[120:123], v[72:75], v[188:191], v[120:123]
	v_mfma_f32_16x16x32_bf16 v[116:119], v[48:51], v[196:199], v[116:119]
	v_mfma_f32_16x16x32_bf16 v[112:115], v[72:75], v[196:199], v[112:115]
	v_mfma_f32_16x16x32_bf16 v[100:103], v[48:51], v[214:217], v[100:103]
	v_mfma_f32_16x16x32_bf16 v[96:99], v[72:75], v[214:217], v[96:99]
	v_mfma_f32_16x16x32_bf16 v[140:143], v[52:55], v[184:187], v[140:143]
	v_mfma_f32_16x16x32_bf16 v[136:139], v[76:79], v[184:187], v[136:139]
	v_mfma_f32_16x16x32_bf16 v[124:127], v[52:55], v[192:195], v[124:127]
	v_mfma_f32_16x16x32_bf16 v[120:123], v[76:79], v[192:195], v[120:123]
	v_mfma_f32_16x16x32_bf16 v[116:119], v[52:55], v[210:213], v[116:119]
	v_mfma_f32_16x16x32_bf16 v[112:115], v[76:79], v[210:213], v[112:115]
	v_mfma_f32_16x16x32_bf16 v[100:103], v[52:55], v[218:221], v[100:103]
	v_mfma_f32_16x16x32_bf16 v[96:99], v[76:79], v[218:221], v[96:99]
	v_mfma_f32_16x16x32_bf16 v[132:135], v[162:165], v[180:183], v[132:135]
	v_mfma_f32_16x16x32_bf16 v[128:131], v[172:175], v[180:183], v[128:131]
	v_mfma_f32_16x16x32_bf16 v[108:111], v[162:165], v[188:191], v[108:111]
	v_mfma_f32_16x16x32_bf16 v[104:107], v[172:175], v[188:191], v[104:107]
	v_mfma_f32_16x16x32_bf16 v[92:95], v[162:165], v[196:199], v[92:95]
	v_mfma_f32_16x16x32_bf16 v[88:91], v[172:175], v[196:199], v[88:91]
	v_mfma_f32_16x16x32_bf16 v[84:87], v[162:165], v[214:217], v[84:87]
	v_mfma_f32_16x16x32_bf16 v[80:83], v[172:175], v[214:217], v[80:83]
	v_mfma_f32_16x16x32_bf16 v[132:135], v[168:171], v[184:187], v[132:135]
	v_mfma_f32_16x16x32_bf16 v[128:131], v[176:179], v[184:187], v[128:131]
	v_mfma_f32_16x16x32_bf16 v[108:111], v[168:171], v[192:195], v[108:111]
	v_mfma_f32_16x16x32_bf16 v[104:107], v[176:179], v[192:195], v[104:107]
	v_mfma_f32_16x16x32_bf16 v[92:95], v[168:171], v[210:213], v[92:95]
	v_mfma_f32_16x16x32_bf16 v[88:91], v[176:179], v[210:213], v[88:91]
	v_mfma_f32_16x16x32_bf16 v[84:87], v[168:171], v[218:221], v[84:87]
	v_mfma_f32_16x16x32_bf16 v[80:83], v[176:179], v[218:221], v[80:83]
	s_setprio 0
	s_barrier
	s_add_i32 s40, s40, s22
	v_lshl_add_u64 v[154:155], s[14:15], 0, v[160:161]
	s_mov_b32 m0, s40
	ds_read_b128 v[180:183], v159 offset:16384
	ds_read_b128 v[184:187], v159 offset:17408
	ds_read_b128 v[188:191], v159 offset:18432
	ds_read_b128 v[192:195], v159 offset:19456
	ds_read_b128 v[196:199], v159 offset:20480
	ds_read_b128 v[210:213], v159 offset:21504
	ds_read_b128 v[214:217], v159 offset:22528
	ds_read_b128 v[218:221], v159 offset:23552
	global_load_lds_dwordx4 v[154:155], off
	s_add_i32 m0, s40, 0x2000
	s_add_u32 s40, s14, 0x160000
	v_lshl_add_u64 v[222:223], s[14:15], 0, v[144:145]
	s_addc_u32 s41, s15, 0
	s_add_i32 s42, s42, s22
	global_load_lds_dwordx4 v[222:223], off
	v_lshl_add_u64 v[224:225], s[40:41], 0, v[160:161]
	s_mov_b32 m0, s42
	v_lshl_add_u64 v[226:227], s[16:17], 0, v[146:147]
	global_load_lds_dwordx4 v[224:225], off
	v_lshl_add_u64 v[224:225], s[40:41], 0, v[144:145]
	s_add_i32 m0, s42, 0x2000
	s_nop 0
	global_load_lds_dwordx4 v[224:225], off
	v_lshl_add_u64 v[224:225], s[16:17], 0, v[148:149]
	s_mov_b32 m0, s23
	s_nop 0
	global_load_lds_dwordx4 v[224:225], off
	s_mov_b32 m0, s24
	s_nop 0
	global_load_lds_dwordx4 v[226:227], off
	s_waitcnt vmcnt(8)
	s_waitcnt lgkmcnt(0)
	s_barrier
; #define PG8_STAGE(bufoff, gbase, voff) do { _Pragma("unroll") for (int _i = 0; _i < 2; ++_i) \
;         __builtin_amdgcn_global_load_lds((const unsigned*)((const char*)(gbase) + (voff)[_i]), (LAS unsigned*)(lds + (bufoff) + ldsw + _i * 8192), 16, 0, 0); } while (0)
; #define PG8_LDA(dst, b, h) do { _Pragma("unroll") for (int m = 0; m < 4; ++m) _Pragma("unroll") for (int k = 0; k < 2; ++k) dst[m][k] = *(const LAS bf16x8*)(lds + PG8_SA(b, h) + aoff + m * 2048 + k * 1024); } while (0)
; #define PG8_LDB(dst, b, h) do { _Pragma("unroll") for (int n = 0; n < 2; ++n) _Pragma("unroll") for (int k = 0; k < 2; ++k) dst[n][k] = *(const LAS bf16x8*)(lds + PG8_SB(b, h) + boff + n * 2048 + k * 1024); } while (0)
; #define PG8_MMA(ai, bj, At, Bt) do { __builtin_amdgcn_s_setprio(1); _Pragma("unroll") for (int m = 0; m < 4; ++m) _Pragma("unroll") for (int n = 0; n < 2; ++n) _Pragma("unroll") for (int k = 0; k < 2; ++k) \
;         acc[ai][bj][m][n] = __builtin_amdgcn_mfma_f32_16x16x32_bf16(Bt[n][k], At[m][k], acc[ai][bj][m][n], 0, 0, 0); __builtin_amdgcn_s_setprio(0); } while (0)
; #define PG8_WAIT_V(n) asm volatile("s_waitcnt vmcnt(" #n ")" ::: "memory")
; #define PG8_WAIT_L(n) asm volatile("s_waitcnt lgkmcnt(" #n ")" ::: "memory")
; #define PG8_BAR __builtin_amdgcn_s_barrier()
; #define PG8_SCHED __builtin_amdgcn_sched_barrier(0)
; template <class Epi, class Sched>
; DI void gemm_phase(const int wv, LAS unsigned char* lds, const int lda, const int ldb, const int K, const Sched& S, const Epi& E) {
;     ...
;             PG8_WAIT_V(8); PG8_WAIT_L(0); PG8_BAR; PG8_MMA(1, 0, At, B0); PG8_MMA(1, 1, At, B1); PG8_BAR; PG8_SCHED;
;             PG8_LDB(B0, 1, 0); PG8_LDB(B1, 1, 1); PG8_SCHED; PG8_LDA(At, 1, 0); PG8_STAGE(PG8_SA(0, 1), a2 + hstepA, voffA);
;             PG8_WAIT_V(8); PG8_WAIT_L(0); PG8_BAR; PG8_MMA(0, 0, At, B0); PG8_MMA(0, 1, At, B1); PG8_BAR; PG8_SCHED;
	s_setprio 1
	s_waitcnt lgkmcnt(0)
	v_mfma_f32_16x16x32_bf16 v[68:71], v[48:51], v[180:183], v[68:71]
	v_mfma_f32_16x16x32_bf16 v[64:67], v[72:75], v[180:183], v[64:67]
	v_mfma_f32_16x16x32_bf16 v[44:47], v[48:51], v[188:191], v[44:47]
	v_mfma_f32_16x16x32_bf16 v[40:43], v[72:75], v[188:191], v[40:43]
	v_mfma_f32_16x16x32_bf16 v[28:31], v[48:51], v[196:199], v[28:31]
	v_mfma_f32_16x16x32_bf16 v[24:27], v[72:75], v[196:199], v[24:27]
	v_mfma_f32_16x16x32_bf16 v[12:15], v[48:51], v[214:217], v[12:15]
	v_mfma_f32_16x16x32_bf16 v[8:11], v[72:75], v[214:217], v[8:11]
	v_mfma_f32_16x16x32_bf16 v[68:71], v[52:55], v[184:187], v[68:71]
	v_mfma_f32_16x16x32_bf16 v[64:67], v[76:79], v[184:187], v[64:67]
	v_mfma_f32_16x16x32_bf16 v[44:47], v[52:55], v[192:195], v[44:47]
	v_mfma_f32_16x16x32_bf16 v[40:43], v[76:79], v[192:195], v[40:43]
	v_mfma_f32_16x16x32_bf16 v[28:31], v[52:55], v[210:213], v[28:31]
	v_mfma_f32_16x16x32_bf16 v[24:27], v[76:79], v[210:213], v[24:27]
	v_mfma_f32_16x16x32_bf16 v[12:15], v[52:55], v[218:221], v[12:15]
	v_mfma_f32_16x16x32_bf16 v[8:11], v[76:79], v[218:221], v[8:11]
	v_mfma_f32_16x16x32_bf16 v[36:39], v[162:165], v[188:191], v[36:39]
	v_mfma_f32_16x16x32_bf16 v[32:35], v[172:175], v[188:191], v[32:35]
	v_mfma_f32_16x16x32_bf16 v[20:23], v[162:165], v[196:199], v[20:23]
	v_mfma_f32_16x16x32_bf16 v[16:19], v[172:175], v[196:199], v[16:19]
	v_mfma_f32_16x16x32_bf16 v[4:7], v[162:165], v[214:217], v[4:7]
	v_mfma_f32_16x16x32_bf16 v[0:3], v[172:175], v[214:217], v[0:3]
	v_mfma_f32_16x16x32_bf16 v[48:51], v[162:165], v[180:183], v[60:63]
	v_mfma_f32_16x16x32_bf16 v[52:55], v[172:175], v[180:183], v[56:59]
	v_mfma_f32_16x16x32_bf16 v[36:39], v[168:171], v[192:195], v[36:39]
	v_mfma_f32_16x16x32_bf16 v[32:35], v[176:179], v[192:195], v[32:35]
	v_mfma_f32_16x16x32_bf16 v[20:23], v[168:171], v[210:213], v[20:23]
	v_mfma_f32_16x16x32_bf16 v[16:19], v[176:179], v[210:213], v[16:19]
	v_mfma_f32_16x16x32_bf16 v[4:7], v[168:171], v[218:221], v[4:7]
	v_mfma_f32_16x16x32_bf16 v[0:3], v[176:179], v[218:221], v[0:3]
	v_mfma_f32_16x16x32_bf16 v[48:51], v[168:171], v[184:187], v[48:51]
	v_mfma_f32_16x16x32_bf16 v[52:55], v[176:179], v[184:187], v[52:55]
	s_setprio 0
	s_barrier
	s_add_i32 s40, 0, 0x18000
	s_add_i32 s41, 0, 0x1c000
	v_add_u32_e32 v76, s40, v157
	v_add_u32_e32 v176, s41, v157
	ds_read_b128 v[56:59], v76
	ds_read_b128 v[60:63], v76 offset:1024
	ds_read_b128 v[72:75], v76 offset:2048
	ds_read_b128 v[76:79], v76 offset:3072
	ds_read_b128 v[162:165], v176
	ds_read_b128 v[168:171], v176 offset:1024
	ds_read_b128 v[172:175], v176 offset:2048
	ds_read_b128 v[176:179], v176 offset:3072
	s_add_u32 s16, s16, 0x160000
	s_addc_u32 s17, s17, 0
	s_mov_b32 m0, s25
	v_lshl_add_u64 v[228:229], s[16:17], 0, v[148:149]
	ds_read_b128 v[180:183], v159 offset:32768
	ds_read_b128 v[184:187], v159 offset:33792
	ds_read_b128 v[188:191], v159 offset:34816
	ds_read_b128 v[192:195], v159 offset:35840
	ds_read_b128 v[196:199], v159 offset:36864
	ds_read_b128 v[210:213], v159 offset:37888
	ds_read_b128 v[214:217], v159 offset:38912
	ds_read_b128 v[218:221], v159 offset:39936
	global_load_lds_dwordx4 v[228:229], off
	v_lshl_add_u64 v[228:229], s[16:17], 0, v[146:147]
	s_mov_b32 m0, s26
	s_nop 0
	global_load_lds_dwordx4 v[228:229], off
	s_waitcnt vmcnt(8)
	s_waitcnt lgkmcnt(0)
	s_barrier
	s_setprio 1
	s_waitcnt lgkmcnt(0)
	v_mfma_f32_16x16x32_bf16 v[140:143], v[56:59], v[180:183], v[140:143]
	v_mfma_f32_16x16x32_bf16 v[136:139], v[72:75], v[180:183], v[136:139]
	v_mfma_f32_16x16x32_bf16 v[124:127], v[56:59], v[188:191], v[124:127]
	v_mfma_f32_16x16x32_bf16 v[120:123], v[72:75], v[188:191], v[120:123]
	v_mfma_f32_16x16x32_bf16 v[116:119], v[56:59], v[196:199], v[116:119]
	v_mfma_f32_16x16x32_bf16 v[112:115], v[72:75], v[196:199], v[112:115]
	v_mfma_f32_16x16x32_bf16 v[100:103], v[56:59], v[214:217], v[100:103]
	v_mfma_f32_16x16x32_bf16 v[96:99], v[72:75], v[214:217], v[96:99]
	v_mfma_f32_16x16x32_bf16 v[140:143], v[60:63], v[184:187], v[140:143]
	v_mfma_f32_16x16x32_bf16 v[136:139], v[76:79], v[184:187], v[136:139]
	v_mfma_f32_16x16x32_bf16 v[124:127], v[60:63], v[192:195], v[124:127]
	v_mfma_f32_16x16x32_bf16 v[120:123], v[76:79], v[192:195], v[120:123]
	v_mfma_f32_16x16x32_bf16 v[116:119], v[60:63], v[210:213], v[116:119]
	v_mfma_f32_16x16x32_bf16 v[112:115], v[76:79], v[210:213], v[112:115]
	v_mfma_f32_16x16x32_bf16 v[100:103], v[60:63], v[218:221], v[100:103]
	v_mfma_f32_16x16x32_bf16 v[96:99], v[76:79], v[218:221], v[96:99]
	v_mfma_f32_16x16x32_bf16 v[132:135], v[162:165], v[180:183], v[132:135]
	v_mfma_f32_16x16x32_bf16 v[128:131], v[172:175], v[180:183], v[128:131]
	v_mfma_f32_16x16x32_bf16 v[108:111], v[162:165], v[188:191], v[108:111]
	v_mfma_f32_16x16x32_bf16 v[104:107], v[172:175], v[188:191], v[104:107]
	v_mfma_f32_16x16x32_bf16 v[92:95], v[162:165], v[196:199], v[92:95]
	v_mfma_f32_16x16x32_bf16 v[88:91], v[172:175], v[196:199], v[88:91]
	v_mfma_f32_16x16x32_bf16 v[84:87], v[162:165], v[214:217], v[84:87]
	v_mfma_f32_16x16x32_bf16 v[80:83], v[172:175], v[214:217], v[80:83]
	v_mfma_f32_16x16x32_bf16 v[132:135], v[168:171], v[184:187], v[132:135]
	v_mfma_f32_16x16x32_bf16 v[128:131], v[176:179], v[184:187], v[128:131]
	v_mfma_f32_16x16x32_bf16 v[108:111], v[168:171], v[192:195], v[108:111]
	v_mfma_f32_16x16x32_bf16 v[104:107], v[176:179], v[192:195], v[104:107]
	v_mfma_f32_16x16x32_bf16 v[92:95], v[168:171], v[210:213], v[92:95]
	v_mfma_f32_16x16x32_bf16 v[88:91], v[176:179], v[210:213], v[88:91]
	v_mfma_f32_16x16x32_bf16 v[84:87], v[168:171], v[218:221], v[84:87]
	v_mfma_f32_16x16x32_bf16 v[80:83], v[176:179], v[218:221], v[80:83]
	s_setprio 0
	s_barrier
; #define PG8_STAGE(bufoff, gbase, voff) do { _Pragma("unroll") for (int _i = 0; _i < 2; ++_i) \
;         __builtin_amdgcn_global_load_lds((const unsigned*)((const char*)(gbase) + (voff)[_i]), (LAS unsigned*)(lds + (bufoff) + ldsw + _i * 8192), 16, 0, 0); } while (0)
; #define PG8_LDA(dst, b, h) do { _Pragma("unroll") for (int m = 0; m < 4; ++m) _Pragma("unroll") for (int k = 0; k < 2; ++k) dst[m][k] = *(const LAS bf16x8*)(lds + PG8_SA(b, h) + aoff + m * 2048 + k * 1024); } while (0)
; #define PG8_MMA(ai, bj, At, Bt) do { __builtin_amdgcn_s_setprio(1); _Pragma("unroll") for (int m = 0; m < 4; ++m) _Pragma("unroll") for (int n = 0; n < 2; ++n) _Pragma("unroll") for (int k = 0; k < 2; ++k) \
;         acc[ai][bj][m][n] = __builtin_amdgcn_mfma_f32_16x16x32_bf16(Bt[n][k], At[m][k], acc[ai][bj][m][n], 0, 0, 0); __builtin_amdgcn_s_setprio(0); } while (0)
; #define PG8_WAIT_V(n) asm volatile("s_waitcnt vmcnt(" #n ")" ::: "memory")
; #define PG8_WAIT_L(n) asm volatile("s_waitcnt lgkmcnt(" #n ")" ::: "memory")
; #define PG8_BAR __builtin_amdgcn_s_barrier()
; #define PG8_SCHED __builtin_amdgcn_sched_barrier(0)
; template <class Epi, class Sched>
; DI void gemm_phase(const int wv, LAS unsigned char* lds, const int lda, const int ldb, const int K, const Sched& S, const Epi& E) {
;     ...
;             PG8_LDA(At, 1, 1); PG8_STAGE(PG8_SB(1, 0), b3, voffB); PG8_STAGE(PG8_SB(1, 1), b3 + hstepB, voffB); PG8_STAGE(PG8_SA(1, 0), a3, voffA);
;             PG8_WAIT_V(8); PG8_WAIT_L(0); PG8_BAR; PG8_MMA(1, 0, At, B0); PG8_MMA(1, 1, At, B1); PG8_BAR; PG8_SCHED;
;         }
;         if (wr == 0) PG8_BAR;
	s_add_i32 s16, s40, s22
	v_lshl_add_u64 v[154:155], v[154:155], 0, s[78:79]
	s_mov_b32 m0, s16
	ds_read_b128 v[180:183], v159 offset:49152
	ds_read_b128 v[184:187], v159 offset:50176
	ds_read_b128 v[188:191], v159 offset:51200
	ds_read_b128 v[192:195], v159 offset:52224
	ds_read_b128 v[196:199], v159 offset:53248
	ds_read_b128 v[210:213], v159 offset:54272
	ds_read_b128 v[214:217], v159 offset:55296
	ds_read_b128 v[218:221], v159 offset:56320
	global_load_lds_dwordx4 v[154:155], off
	s_add_i32 m0, s16, 0x2000
	s_add_u32 s14, s14, 0x160080
	v_lshl_add_u64 v[154:155], v[222:223], 0, s[78:79]
	s_addc_u32 s15, s15, 0
	s_add_i32 s16, s41, s22
	global_load_lds_dwordx4 v[154:155], off
	v_lshl_add_u64 v[154:155], s[14:15], 0, v[160:161]
	s_mov_b32 m0, s16
	s_nop 0
	global_load_lds_dwordx4 v[154:155], off
	v_lshl_add_u64 v[154:155], s[14:15], 0, v[144:145]
	s_add_i32 m0, s16, 0x2000
	s_nop 0
	global_load_lds_dwordx4 v[154:155], off
	v_lshl_add_u64 v[154:155], v[224:225], 0, s[78:79]
	s_mov_b32 m0, s29
	s_nop 0
	global_load_lds_dwordx4 v[154:155], off
	v_lshl_add_u64 v[154:155], v[226:227], 0, s[78:79]
	s_mov_b32 m0, s30
	s_nop 0
	global_load_lds_dwordx4 v[154:155], off
	s_waitcnt vmcnt(8)
	s_waitcnt lgkmcnt(0)
	s_barrier
	s_setprio 1
	s_waitcnt lgkmcnt(0)
	v_mfma_f32_16x16x32_bf16 v[68:71], v[56:59], v[180:183], v[68:71]
	v_mfma_f32_16x16x32_bf16 v[64:67], v[72:75], v[180:183], v[64:67]
	v_mfma_f32_16x16x32_bf16 v[44:47], v[56:59], v[188:191], v[44:47]
	v_mfma_f32_16x16x32_bf16 v[40:43], v[72:75], v[188:191], v[40:43]
	v_mfma_f32_16x16x32_bf16 v[28:31], v[56:59], v[196:199], v[28:31]
	v_mfma_f32_16x16x32_bf16 v[24:27], v[72:75], v[196:199], v[24:27]
	v_mfma_f32_16x16x32_bf16 v[12:15], v[56:59], v[214:217], v[12:15]
	v_mfma_f32_16x16x32_bf16 v[8:11], v[72:75], v[214:217], v[8:11]
	v_mfma_f32_16x16x32_bf16 v[68:71], v[60:63], v[184:187], v[68:71]
	v_mfma_f32_16x16x32_bf16 v[64:67], v[76:79], v[184:187], v[64:67]
	v_mfma_f32_16x16x32_bf16 v[44:47], v[60:63], v[192:195], v[44:47]
	v_mfma_f32_16x16x32_bf16 v[40:43], v[76:79], v[192:195], v[40:43]
	v_mfma_f32_16x16x32_bf16 v[28:31], v[60:63], v[210:213], v[28:31]
	v_mfma_f32_16x16x32_bf16 v[24:27], v[76:79], v[210:213], v[24:27]
	v_mfma_f32_16x16x32_bf16 v[12:15], v[60:63], v[218:221], v[12:15]
	v_mfma_f32_16x16x32_bf16 v[8:11], v[76:79], v[218:221], v[8:11]
	v_mfma_f32_16x16x32_bf16 v[48:51], v[162:165], v[180:183], v[48:51]
	v_mfma_f32_16x16x32_bf16 v[60:63], v[168:171], v[184:187], v[48:51]
	v_mfma_f32_16x16x32_bf16 v[48:51], v[172:175], v[180:183], v[52:55]
	v_mfma_f32_16x16x32_bf16 v[36:39], v[162:165], v[188:191], v[36:39]
	v_mfma_f32_16x16x32_bf16 v[32:35], v[172:175], v[188:191], v[32:35]
	v_mfma_f32_16x16x32_bf16 v[20:23], v[162:165], v[196:199], v[20:23]
	v_mfma_f32_16x16x32_bf16 v[16:19], v[172:175], v[196:199], v[16:19]
	v_mfma_f32_16x16x32_bf16 v[4:7], v[162:165], v[214:217], v[4:7]
	v_mfma_f32_16x16x32_bf16 v[0:3], v[172:175], v[214:217], v[0:3]
	v_mfma_f32_16x16x32_bf16 v[56:59], v[176:179], v[184:187], v[48:51]
	v_mfma_f32_16x16x32_bf16 v[36:39], v[168:171], v[192:195], v[36:39]
	v_mfma_f32_16x16x32_bf16 v[32:35], v[176:179], v[192:195], v[32:35]
	v_mfma_f32_16x16x32_bf16 v[20:23], v[168:171], v[210:213], v[20:23]
	v_mfma_f32_16x16x32_bf16 v[16:19], v[176:179], v[210:213], v[16:19]
	v_mfma_f32_16x16x32_bf16 v[4:7], v[168:171], v[218:221], v[4:7]
	v_mfma_f32_16x16x32_bf16 v[0:3], v[176:179], v[218:221], v[0:3]
	s_setprio 0
	s_barrier
	s_add_i32 s39, s39, 2
	s_add_u32 s37, s37, 0x100
	s_addc_u32 s38, s38, 0
	s_add_u32 s12, s12, 0x100
	s_addc_u32 s13, s13, 0
	s_cmpk_gt_u32 s39, 0x55
	s_cbranch_scc0 .LBB0_906
	s_and_b64 vcc, exec, s[6:7]
	s_cbranch_vccz .LBB0_909
	s_barrier
